# hgrn_c row loop: 8-row register prefetch queue replaces 96 serialized global loads per job
# speedup vs baseline: 1.0507x; 1.0507x over previous
.LBB0_635:
	s_xor_b64 s[34:35], s[44:45], -1
	s_or_b32 s12, s53, s52
	s_and_b64 s[16:17], s[44:45], exec
	s_mov_b32 s13, 0x125ba000
	s_cselect_b32 s30, 0x10dba000, s13
	s_mov_b32 s13, s31
	s_lshl_b64 s[16:17], s[12:13], 15
	s_lshl_b64 s[12:13], s[12:13], 9
	v_lshl_add_u64 v[64:65], v[170:171], 0, s[12:13]
	s_and_b64 s[12:13], s[44:45], exec
	s_cselect_b32 s12, 0, 31
	v_lshl_add_u64 v[130:131], v[168:169], 0, s[30:31]
	s_lshl_b32 s30, s12, 10
	s_barrier
	v_lshl_add_u64 v[66:67], v[130:131], 0, s[30:31]
	global_load_dword v134, v[64:65], off
	global_load_ushort v138, v[66:67], off
	s_mul_i32 s30, s12, 0x3b80
	v_lshl_add_u64 v[132:133], v[164:165], 0, s[30:31]
	global_load_ushort v135, v[132:133], off
	v_lshl_add_u64 v[126:127], v[166:167], 0, s[16:17]
	s_movk_i32 s13, 0x2000
	v_add_co_u32_e32 v64, vcc, s13, v126
	v_or_b32_e32 v136, s12, v199
	s_nop 0
	v_addc_co_u32_e32 v65, vcc, 0, v127, vcc
	global_load_dwordx4 v[122:125], v[126:127], off offset:32
	global_load_dwordx4 v[118:121], v[126:127], off offset:64
	global_load_dwordx4 v[114:117], v[126:127], off offset:96
	global_load_dwordx4 v[110:113], v[126:127], off offset:128
	global_load_dwordx4 v[106:109], v[126:127], off offset:160
	global_load_dwordx4 v[102:105], v[126:127], off offset:192
	global_load_dwordx4 v[98:101], v[126:127], off offset:224
	global_load_dwordx4 v[92:95], v[64:65], off
	global_load_dwordx4 v[88:91], v[64:65], off offset:32
	global_load_dwordx4 v[84:87], v[64:65], off offset:64
	global_load_dwordx4 v[80:83], v[64:65], off offset:96
	global_load_dwordx4 v[76:79], v[64:65], off offset:128
	global_load_dwordx4 v[72:75], v[64:65], off offset:160
	global_load_dwordx4 v[68:71], v[64:65], off offset:192
	s_nop 0
	global_load_dwordx4 v[64:67], v[64:65], off offset:224
	s_nop 0
	global_load_dwordx4 v[126:129], v[126:127], off
	v_mad_u64_u32 v[136:137], s[12:13], v136, s23, v[162:163]
	s_mov_b32 s16, 30
	s_and_b64 vcc, exec, s[34:35]
	s_cmp_lg_u64 s[34:35], 0
	s_cselect_b32 s100, -1, 1
	v_lshl_add_u32 v136, v136, 1, 16
	s_waitcnt vmcnt(18)
	v_cndmask_b32_e64 v137, 0, v134, s[38:39]
	s_waitcnt vmcnt(17)
	v_cvt_f32_f16_e32 v139, v138
	v_cndmask_b32_e64 v140, 0, v134, s[40:41]
	v_cndmask_b32_e64 v137, v140, v137, s[44:45]
	s_waitcnt vmcnt(16)
	v_lshlrev_b32_e32 v140, 16, v135
	v_add_f32_e32 v135, v137, v139
	v_mul_f32_e32 v137, 0x3fb8aa3b, v139
	v_sub_f32_e32 v141, v135, v134
	v_rndne_f32_e32 v137, v137
	v_mul_f32_e32 v141, 0x3fb8aa3b, v141
	v_fma_mix_f32 v143, v137, s97, v138 op_sel_hi:[0,0,1]
	v_exp_f32_e32 v141, v141
	v_fmac_f32_e32 v143, 0x3102e308, v137
	v_cvt_i32_f32_e32 v144, v137
	v_fmamk_f32 v145, v143, 0x395133b1, v182
	v_fmaak_f32 v145, v143, v145, 0x3c0887f9
	v_fmaak_f32 v145, v143, v145, 0x3d2aaa81
	v_mul_f32_e32 v140, v141, v140
	v_fmaak_f32 v141, v143, v145, 0x3e2aaaab
	v_ldexp_f32 v144, 1.0, v144
	v_cmp_eq_f32_e64 s[12:13], s94, v137
	v_fma_f32 v141, v143, v141, 0.5
	v_mul_f32_e32 v141, v143, v141
	v_cndmask_b32_e64 v137, v144, v193, s[12:13]
	v_sub_f32_e32 v142, v134, v135
	v_add_f32_e32 v145, -1.0, v137
	v_fmac_f32_e32 v143, v143, v141
	v_mul_f32_e32 v142, 0x3fb8aa3b, v142
	v_fmac_f32_e32 v145, v137, v143
	v_exp_f32_e32 v142, v142
	v_add_f32_e32 v137, v145, v145
	v_cndmask_b32_e64 v137, v145, v137, s[12:13]
	v_cmp_nlt_f32_e64 s[12:13], s95, v139
	v_bfe_u32 v144, v140, 16, 1
	v_add3_u32 v140, v140, v144, s33
	v_cndmask_b32_e64 v137, v194, -v137, s[12:13]
	v_cmp_ngt_f16_e64 s[12:13], s96, v138
	ds_write_b16_d16_hi v136, v140
	s_nop 0
	v_cndmask_b32_e64 v137, 1.0, v137, s[12:13]
	v_mul_f32_e32 v137, v142, v137
	v_bfe_u32 v138, v137, 16, 1
	v_add3_u32 v137, v137, v138, s33
	ds_write_b16_d16_hi v136, v137 offset:17408
	s_cbranch_vccnz .LBB0_637
	global_load_ushort v132, v[132:133], off offset:3072
	s_mov_b32 s16, 1
	s_waitcnt vmcnt(0)
	ds_write_b16 v202, v132 offset:34816
.LBB0_637:
	s_mul_i32 s101, s100, 1
	s_cmp_lt_i32 s100, 0
	s_cselect_b32 s30, 31, 0
	s_add_i32 s101, s101, s30
	s_lshl_b32 s30, s101, 10
	v_lshl_add_u64 v[132:133], v[130:131], 0, s[30:31]
	global_load_ushort v235, v[132:133], off
	s_mul_i32 s30, s101, 0x3b80
	v_lshl_add_u64 v[132:133], v[164:165], 0, s[30:31]
	global_load_ushort v236, v[132:133], off
	global_load_ushort v237, v[132:133], off offset:3072
	s_mul_i32 s101, s100, 2
	s_cmp_lt_i32 s100, 0
	s_cselect_b32 s30, 31, 0
	s_add_i32 s101, s101, s30
	s_lshl_b32 s30, s101, 10
	v_lshl_add_u64 v[132:133], v[130:131], 0, s[30:31]
	global_load_ushort v238, v[132:133], off
	s_mul_i32 s30, s101, 0x3b80
	v_lshl_add_u64 v[132:133], v[164:165], 0, s[30:31]
	global_load_ushort v239, v[132:133], off
	global_load_ushort v240, v[132:133], off offset:3072
	s_mul_i32 s101, s100, 3
	s_cmp_lt_i32 s100, 0
	s_cselect_b32 s30, 31, 0
	s_add_i32 s101, s101, s30
	s_lshl_b32 s30, s101, 10
	v_lshl_add_u64 v[132:133], v[130:131], 0, s[30:31]
	global_load_ushort v241, v[132:133], off
	s_mul_i32 s30, s101, 0x3b80
	v_lshl_add_u64 v[132:133], v[164:165], 0, s[30:31]
	global_load_ushort v242, v[132:133], off
	global_load_ushort v243, v[132:133], off offset:3072
	s_mul_i32 s101, s100, 4
	s_cmp_lt_i32 s100, 0
	s_cselect_b32 s30, 31, 0
	s_add_i32 s101, s101, s30
	s_lshl_b32 s30, s101, 10
	v_lshl_add_u64 v[132:133], v[130:131], 0, s[30:31]
	global_load_ushort v244, v[132:133], off
	s_mul_i32 s30, s101, 0x3b80
	v_lshl_add_u64 v[132:133], v[164:165], 0, s[30:31]
	global_load_ushort v245, v[132:133], off
	global_load_ushort v246, v[132:133], off offset:3072
	s_mul_i32 s101, s100, 5
	s_cmp_lt_i32 s100, 0
	s_cselect_b32 s30, 31, 0
	s_add_i32 s101, s101, s30
	s_lshl_b32 s30, s101, 10
	v_lshl_add_u64 v[132:133], v[130:131], 0, s[30:31]
	global_load_ushort v247, v[132:133], off
	s_mul_i32 s30, s101, 0x3b80
	v_lshl_add_u64 v[132:133], v[164:165], 0, s[30:31]
	global_load_ushort v248, v[132:133], off
	global_load_ushort v249, v[132:133], off offset:3072
	s_mul_i32 s101, s100, 6
	s_cmp_lt_i32 s100, 0
	s_cselect_b32 s30, 31, 0
	s_add_i32 s101, s101, s30
	s_lshl_b32 s30, s101, 10
	v_lshl_add_u64 v[132:133], v[130:131], 0, s[30:31]
	global_load_ushort v250, v[132:133], off
	s_mul_i32 s30, s101, 0x3b80
	v_lshl_add_u64 v[132:133], v[164:165], 0, s[30:31]
	global_load_ushort v251, v[132:133], off
	global_load_ushort v252, v[132:133], off offset:3072
	s_mul_i32 s101, s100, 7
	s_cmp_lt_i32 s100, 0
	s_cselect_b32 s30, 31, 0
	s_add_i32 s101, s101, s30
	s_lshl_b32 s30, s101, 10
	v_lshl_add_u64 v[132:133], v[130:131], 0, s[30:31]
	global_load_ushort v253, v[132:133], off
	s_mul_i32 s30, s101, 0x3b80
	v_lshl_add_u64 v[132:133], v[164:165], 0, s[30:31]
	global_load_ushort v254, v[132:133], off
	global_load_ushort v255, v[132:133], off offset:3072
	s_mul_i32 s101, s100, 8
	s_cmp_lt_i32 s100, 0
	s_cselect_b32 s30, 31, 0
	s_add_i32 s101, s101, s30
	s_lshl_b32 s30, s101, 10
	v_lshl_add_u64 v[132:133], v[130:131], 0, s[30:31]
	global_load_ushort v232, v[132:133], off
	s_mul_i32 s30, s101, 0x3b80
	v_lshl_add_u64 v[132:133], v[164:165], 0, s[30:31]
	global_load_ushort v233, v[132:133], off
	global_load_ushort v234, v[132:133], off offset:3072
	s_waitcnt vmcnt(21)
	v_mov_b32_e32 v138, v235
	v_cvt_f32_f16_e32 v139, v138
	v_lshlrev_b32_e32 v136, 16, v236
	s_cmp_lt_i32 s100, 0
	s_cbranch_scc1 .Lmy_hc_1
	ds_write_b16 v202, v237 offset:34818
.Lmy_hc_1:
	s_mul_i32 s101, s100, 9
	s_cmp_lt_i32 s100, 0
	s_cselect_b32 s30, 31, 0
	s_add_i32 s101, s101, s30
	s_lshl_b32 s30, s101, 10
	v_lshl_add_u64 v[132:133], v[130:131], 0, s[30:31]
	global_load_ushort v235, v[132:133], off
	s_mul_i32 s30, s101, 0x3b80
	v_lshl_add_u64 v[132:133], v[164:165], 0, s[30:31]
	global_load_ushort v236, v[132:133], off
	global_load_ushort v237, v[132:133], off offset:3072
	v_add_f32_e32 v135, v135, v139
	v_sub_f32_e32 v137, v135, v134
	v_mul_f32_e32 v137, 0x3fb8aa3b, v137
	v_exp_f32_e32 v137, v137
	s_nop 0
	v_mul_f32_e32 v136, v137, v136
	v_bfe_u32 v137, v136, 16, 1
	v_add3_u32 v140, v136, v137, s33
	v_or_b32_e32 v136, s16, v199
	v_mad_u64_u32 v[136:137], s[12:13], v136, s23, v[162:163]
	v_mul_f32_e32 v137, 0x3fb8aa3b, v139
	v_lshl_add_u32 v136, v136, 1, 16
	v_rndne_f32_e32 v137, v137
	ds_write_b16_d16_hi v136, v140
	v_fma_mix_f32 v140, v137, s97, v138 op_sel_hi:[0,0,1]
	v_fmac_f32_e32 v140, 0x3102e308, v137
	v_fmamk_f32 v141, v140, 0x395133b1, v182
	v_cmp_eq_f32_e32 vcc, s94, v137
	v_cvt_i32_f32_e32 v137, v137
	v_fmaak_f32 v141, v140, v141, 0x3c0887f9
	v_fmaak_f32 v141, v140, v141, 0x3d2aaa81
	v_fmaak_f32 v141, v140, v141, 0x3e2aaaab
	v_fma_f32 v141, v140, v141, 0.5
	v_ldexp_f32 v137, 1.0, v137
	v_mul_f32_e32 v141, v140, v141
	v_cndmask_b32_e32 v137, v137, v193, vcc
	v_fmac_f32_e32 v140, v140, v141
	v_add_f32_e32 v141, -1.0, v137
	v_fmac_f32_e32 v141, v137, v140
	v_add_f32_e32 v137, v141, v141
	v_cndmask_b32_e32 v137, v141, v137, vcc
	v_cmp_nlt_f32_e32 vcc, s95, v139
	s_mov_b32 s16, 29
	s_nop 0
	v_cndmask_b32_e64 v137, v194, -v137, vcc
	v_cmp_ngt_f16_e32 vcc, s96, v138
	v_sub_f32_e32 v138, v134, v135
	v_mul_f32_e32 v138, 0x3fb8aa3b, v138
	v_exp_f32_e32 v138, v138
	v_cndmask_b32_e32 v137, 1.0, v137, vcc
	s_andn2_b64 vcc, exec, s[44:45]
	v_mul_f32_e32 v137, v138, v137
	v_bfe_u32 v138, v137, 16, 1
	v_add3_u32 v137, v137, v138, s33
	ds_write_b16_d16_hi v136, v137 offset:17408
	v_cndmask_b32_e64 v136, 0, 1, s[44:45]
	v_cmp_ne_u32_e64 s[12:13], 1, v136
	s_cbranch_vccnz .LBB0_639
	s_mov_b32 s16, 2
.LBB0_639:
	s_waitcnt vmcnt(21)
	v_mov_b32_e32 v138, v238
	v_cvt_f32_f16_e32 v139, v138
	v_lshlrev_b32_e32 v136, 16, v239
	s_cmp_lt_i32 s100, 0
	s_cbranch_scc1 .Lmy_hc_2
	ds_write_b16 v202, v240 offset:34820
.Lmy_hc_2:
	s_mul_i32 s101, s100, 10
	s_cmp_lt_i32 s100, 0
	s_cselect_b32 s30, 31, 0
	s_add_i32 s101, s101, s30
	s_lshl_b32 s30, s101, 10
	v_lshl_add_u64 v[132:133], v[130:131], 0, s[30:31]
	global_load_ushort v238, v[132:133], off
	s_mul_i32 s30, s101, 0x3b80
	v_lshl_add_u64 v[132:133], v[164:165], 0, s[30:31]
	global_load_ushort v239, v[132:133], off
	global_load_ushort v240, v[132:133], off offset:3072
	v_add_f32_e32 v135, v135, v139
	v_sub_f32_e32 v137, v135, v134
	v_mul_f32_e32 v137, 0x3fb8aa3b, v137
	v_exp_f32_e32 v137, v137
	s_nop 0
	v_mul_f32_e32 v136, v137, v136
	v_bfe_u32 v137, v136, 16, 1
	v_add3_u32 v140, v136, v137, s33
	v_or_b32_e32 v136, s16, v199
	v_mad_u64_u32 v[136:137], s[16:17], v136, s23, v[162:163]
	v_mul_f32_e32 v137, 0x3fb8aa3b, v139
	v_lshl_add_u32 v136, v136, 1, 16
	v_rndne_f32_e32 v137, v137
	ds_write_b16_d16_hi v136, v140
	v_fma_mix_f32 v140, v137, s97, v138 op_sel_hi:[0,0,1]
	v_fmac_f32_e32 v140, 0x3102e308, v137
	v_fmamk_f32 v141, v140, 0x395133b1, v182
	v_cmp_eq_f32_e32 vcc, s94, v137
	v_cvt_i32_f32_e32 v137, v137
	v_fmaak_f32 v141, v140, v141, 0x3c0887f9
	v_fmaak_f32 v141, v140, v141, 0x3d2aaa81
	v_fmaak_f32 v141, v140, v141, 0x3e2aaaab
	v_fma_f32 v141, v140, v141, 0.5
	v_ldexp_f32 v137, 1.0, v137
	v_mul_f32_e32 v141, v140, v141
	v_cndmask_b32_e32 v137, v137, v193, vcc
	v_fmac_f32_e32 v140, v140, v141
	v_add_f32_e32 v141, -1.0, v137
	v_fmac_f32_e32 v141, v137, v140
	v_add_f32_e32 v137, v141, v141
	v_cndmask_b32_e32 v137, v141, v137, vcc
	v_cmp_nlt_f32_e32 vcc, s95, v139
	s_mov_b32 s16, 28
	s_nop 0
	v_cndmask_b32_e64 v137, v194, -v137, vcc
	v_cmp_ngt_f16_e32 vcc, s96, v138
	v_sub_f32_e32 v138, v134, v135
	v_mul_f32_e32 v138, 0x3fb8aa3b, v138
	v_exp_f32_e32 v138, v138
	v_cndmask_b32_e32 v137, 1.0, v137, vcc
	s_and_b64 vcc, exec, s[12:13]
	v_mul_f32_e32 v137, v138, v137
	v_bfe_u32 v138, v137, 16, 1
	v_add3_u32 v137, v137, v138, s33
	ds_write_b16_d16_hi v136, v137 offset:17408
	s_cbranch_vccnz .LBB0_641
	s_mov_b32 s16, 3
.LBB0_641:
	s_waitcnt vmcnt(21)
	v_mov_b32_e32 v138, v241
	v_cvt_f32_f16_e32 v139, v138
	v_lshlrev_b32_e32 v136, 16, v242
	s_cmp_lt_i32 s100, 0
	s_cbranch_scc1 .Lmy_hc_3
	ds_write_b16 v202, v243 offset:34822
.Lmy_hc_3:
	s_mul_i32 s101, s100, 11
	s_cmp_lt_i32 s100, 0
	s_cselect_b32 s30, 31, 0
	s_add_i32 s101, s101, s30
	s_lshl_b32 s30, s101, 10
	v_lshl_add_u64 v[132:133], v[130:131], 0, s[30:31]
	global_load_ushort v241, v[132:133], off
	s_mul_i32 s30, s101, 0x3b80
	v_lshl_add_u64 v[132:133], v[164:165], 0, s[30:31]
	global_load_ushort v242, v[132:133], off
	global_load_ushort v243, v[132:133], off offset:3072
	v_add_f32_e32 v135, v135, v139
	v_sub_f32_e32 v137, v135, v134
	v_mul_f32_e32 v137, 0x3fb8aa3b, v137
	v_exp_f32_e32 v137, v137
	s_nop 0
	v_mul_f32_e32 v136, v137, v136
	v_bfe_u32 v137, v136, 16, 1
	v_add3_u32 v140, v136, v137, s33
	v_or_b32_e32 v136, s16, v199
	v_mad_u64_u32 v[136:137], s[16:17], v136, s23, v[162:163]
	v_mul_f32_e32 v137, 0x3fb8aa3b, v139
	v_lshl_add_u32 v136, v136, 1, 16
	v_rndne_f32_e32 v137, v137
	ds_write_b16_d16_hi v136, v140
	v_fma_mix_f32 v140, v137, s97, v138 op_sel_hi:[0,0,1]
	v_fmac_f32_e32 v140, 0x3102e308, v137
	v_fmamk_f32 v141, v140, 0x395133b1, v182
	v_cmp_eq_f32_e32 vcc, s94, v137
	v_cvt_i32_f32_e32 v137, v137
	v_fmaak_f32 v141, v140, v141, 0x3c0887f9
	v_fmaak_f32 v141, v140, v141, 0x3d2aaa81
	v_fmaak_f32 v141, v140, v141, 0x3e2aaaab
	v_fma_f32 v141, v140, v141, 0.5
	v_ldexp_f32 v137, 1.0, v137
	v_mul_f32_e32 v141, v140, v141
	v_cndmask_b32_e32 v137, v137, v193, vcc
	v_fmac_f32_e32 v140, v140, v141
	v_add_f32_e32 v141, -1.0, v137
	v_fmac_f32_e32 v141, v137, v140
	v_add_f32_e32 v137, v141, v141
	v_cndmask_b32_e32 v137, v141, v137, vcc
	v_cmp_nlt_f32_e32 vcc, s95, v139
	s_mov_b32 s16, 27
	s_nop 0
	v_cndmask_b32_e64 v137, v194, -v137, vcc
	v_cmp_ngt_f16_e32 vcc, s96, v138
	v_sub_f32_e32 v138, v134, v135
	v_mul_f32_e32 v138, 0x3fb8aa3b, v138
	v_exp_f32_e32 v138, v138
	v_cndmask_b32_e32 v137, 1.0, v137, vcc
	s_and_b64 vcc, exec, s[12:13]
	v_mul_f32_e32 v137, v138, v137
	v_bfe_u32 v138, v137, 16, 1
	v_add3_u32 v137, v137, v138, s33
	ds_write_b16_d16_hi v136, v137 offset:17408
	s_cbranch_vccnz .LBB0_643
	s_mov_b32 s16, 4
.LBB0_643:
	s_waitcnt vmcnt(21)
	v_mov_b32_e32 v138, v244
	v_cvt_f32_f16_e32 v139, v138
	v_lshlrev_b32_e32 v136, 16, v245
	s_cmp_lt_i32 s100, 0
	s_cbranch_scc1 .Lmy_hc_4
	ds_write_b16 v202, v246 offset:34824
.Lmy_hc_4:
	s_mul_i32 s101, s100, 12
	s_cmp_lt_i32 s100, 0
	s_cselect_b32 s30, 31, 0
	s_add_i32 s101, s101, s30
	s_lshl_b32 s30, s101, 10
	v_lshl_add_u64 v[132:133], v[130:131], 0, s[30:31]
	global_load_ushort v244, v[132:133], off
	s_mul_i32 s30, s101, 0x3b80
	v_lshl_add_u64 v[132:133], v[164:165], 0, s[30:31]
	global_load_ushort v245, v[132:133], off
	global_load_ushort v246, v[132:133], off offset:3072
	v_add_f32_e32 v135, v135, v139
	v_sub_f32_e32 v137, v135, v134
	v_mul_f32_e32 v137, 0x3fb8aa3b, v137
	v_exp_f32_e32 v137, v137
	s_nop 0
	v_mul_f32_e32 v136, v137, v136
	v_bfe_u32 v137, v136, 16, 1
	v_add3_u32 v140, v136, v137, s33
	v_or_b32_e32 v136, s16, v199
	v_mad_u64_u32 v[136:137], s[16:17], v136, s23, v[162:163]
	v_mul_f32_e32 v137, 0x3fb8aa3b, v139
	v_lshl_add_u32 v136, v136, 1, 16
	v_rndne_f32_e32 v137, v137
	ds_write_b16_d16_hi v136, v140
	v_fma_mix_f32 v140, v137, s97, v138 op_sel_hi:[0,0,1]
	v_fmac_f32_e32 v140, 0x3102e308, v137
	v_fmamk_f32 v141, v140, 0x395133b1, v182
	v_cmp_eq_f32_e32 vcc, s94, v137
	v_cvt_i32_f32_e32 v137, v137
	v_fmaak_f32 v141, v140, v141, 0x3c0887f9
	v_fmaak_f32 v141, v140, v141, 0x3d2aaa81
	v_fmaak_f32 v141, v140, v141, 0x3e2aaaab
	v_fma_f32 v141, v140, v141, 0.5
	v_ldexp_f32 v137, 1.0, v137
	v_mul_f32_e32 v141, v140, v141
	v_cndmask_b32_e32 v137, v137, v193, vcc
	v_fmac_f32_e32 v140, v140, v141
	v_add_f32_e32 v141, -1.0, v137
	v_fmac_f32_e32 v141, v137, v140
	v_add_f32_e32 v137, v141, v141
	v_cndmask_b32_e32 v137, v141, v137, vcc
	v_cmp_nlt_f32_e32 vcc, s95, v139
	s_mov_b32 s16, 26
	s_nop 0
	v_cndmask_b32_e64 v137, v194, -v137, vcc
	v_cmp_ngt_f16_e32 vcc, s96, v138
	v_sub_f32_e32 v138, v134, v135
	v_mul_f32_e32 v138, 0x3fb8aa3b, v138
	v_exp_f32_e32 v138, v138
	v_cndmask_b32_e32 v137, 1.0, v137, vcc
	s_and_b64 vcc, exec, s[12:13]
	v_mul_f32_e32 v137, v138, v137
	v_bfe_u32 v138, v137, 16, 1
	v_add3_u32 v137, v137, v138, s33
	ds_write_b16_d16_hi v136, v137 offset:17408
	s_cbranch_vccnz .LBB0_645
	s_mov_b32 s16, 5
.LBB0_645:
	s_waitcnt vmcnt(21)
	v_mov_b32_e32 v138, v247
	v_cvt_f32_f16_e32 v139, v138
	v_lshlrev_b32_e32 v136, 16, v248
	s_cmp_lt_i32 s100, 0
	s_cbranch_scc1 .Lmy_hc_5
	ds_write_b16 v202, v249 offset:34826
.Lmy_hc_5:
	s_mul_i32 s101, s100, 13
	s_cmp_lt_i32 s100, 0
	s_cselect_b32 s30, 31, 0
	s_add_i32 s101, s101, s30
	s_lshl_b32 s30, s101, 10
	v_lshl_add_u64 v[132:133], v[130:131], 0, s[30:31]
	global_load_ushort v247, v[132:133], off
	s_mul_i32 s30, s101, 0x3b80
	v_lshl_add_u64 v[132:133], v[164:165], 0, s[30:31]
	global_load_ushort v248, v[132:133], off
	global_load_ushort v249, v[132:133], off offset:3072
	v_add_f32_e32 v135, v135, v139
	v_sub_f32_e32 v137, v135, v134
	v_mul_f32_e32 v137, 0x3fb8aa3b, v137
	v_exp_f32_e32 v137, v137
	s_nop 0
	v_mul_f32_e32 v136, v137, v136
	v_bfe_u32 v137, v136, 16, 1
	v_add3_u32 v140, v136, v137, s33
	v_or_b32_e32 v136, s16, v199
	v_mad_u64_u32 v[136:137], s[16:17], v136, s23, v[162:163]
	v_mul_f32_e32 v137, 0x3fb8aa3b, v139
	v_lshl_add_u32 v136, v136, 1, 16
	v_rndne_f32_e32 v137, v137
	ds_write_b16_d16_hi v136, v140
	v_fma_mix_f32 v140, v137, s97, v138 op_sel_hi:[0,0,1]
	v_fmac_f32_e32 v140, 0x3102e308, v137
	v_fmamk_f32 v141, v140, 0x395133b1, v182
	v_cmp_eq_f32_e32 vcc, s94, v137
	v_cvt_i32_f32_e32 v137, v137
	v_fmaak_f32 v141, v140, v141, 0x3c0887f9
	v_fmaak_f32 v141, v140, v141, 0x3d2aaa81
	v_fmaak_f32 v141, v140, v141, 0x3e2aaaab
	v_fma_f32 v141, v140, v141, 0.5
	v_ldexp_f32 v137, 1.0, v137
	v_mul_f32_e32 v141, v140, v141
	v_cndmask_b32_e32 v137, v137, v193, vcc
	v_fmac_f32_e32 v140, v140, v141
	v_add_f32_e32 v141, -1.0, v137
	v_fmac_f32_e32 v141, v137, v140
	v_add_f32_e32 v137, v141, v141
	v_cndmask_b32_e32 v137, v141, v137, vcc
	v_cmp_nlt_f32_e32 vcc, s95, v139
	s_mov_b32 s16, 25
	s_nop 0
	v_cndmask_b32_e64 v137, v194, -v137, vcc
	v_cmp_ngt_f16_e32 vcc, s96, v138
	v_sub_f32_e32 v138, v134, v135
	v_mul_f32_e32 v138, 0x3fb8aa3b, v138
	v_exp_f32_e32 v138, v138
	v_cndmask_b32_e32 v137, 1.0, v137, vcc
	s_and_b64 vcc, exec, s[12:13]
	v_mul_f32_e32 v137, v138, v137
	v_bfe_u32 v138, v137, 16, 1
	v_add3_u32 v137, v137, v138, s33
	ds_write_b16_d16_hi v136, v137 offset:17408
	s_cbranch_vccnz .LBB0_647
	s_mov_b32 s16, 6
.LBB0_647:
	s_waitcnt vmcnt(21)
	v_mov_b32_e32 v138, v250
	v_cvt_f32_f16_e32 v139, v138
	v_lshlrev_b32_e32 v136, 16, v251
	s_cmp_lt_i32 s100, 0
	s_cbranch_scc1 .Lmy_hc_6
	ds_write_b16 v202, v252 offset:34828
.Lmy_hc_6:
	s_mul_i32 s101, s100, 14
	s_cmp_lt_i32 s100, 0
	s_cselect_b32 s30, 31, 0
	s_add_i32 s101, s101, s30
	s_lshl_b32 s30, s101, 10
	v_lshl_add_u64 v[132:133], v[130:131], 0, s[30:31]
	global_load_ushort v250, v[132:133], off
	s_mul_i32 s30, s101, 0x3b80
	v_lshl_add_u64 v[132:133], v[164:165], 0, s[30:31]
	global_load_ushort v251, v[132:133], off
	global_load_ushort v252, v[132:133], off offset:3072
	v_add_f32_e32 v135, v135, v139
	v_sub_f32_e32 v137, v135, v134
	v_mul_f32_e32 v137, 0x3fb8aa3b, v137
	v_exp_f32_e32 v137, v137
	s_nop 0
	v_mul_f32_e32 v136, v137, v136
	v_bfe_u32 v137, v136, 16, 1
	v_add3_u32 v140, v136, v137, s33
	v_or_b32_e32 v136, s16, v199
	v_mad_u64_u32 v[136:137], s[16:17], v136, s23, v[162:163]
	v_mul_f32_e32 v137, 0x3fb8aa3b, v139
	v_lshl_add_u32 v136, v136, 1, 16
	v_rndne_f32_e32 v137, v137
	ds_write_b16_d16_hi v136, v140
	v_fma_mix_f32 v140, v137, s97, v138 op_sel_hi:[0,0,1]
	v_fmac_f32_e32 v140, 0x3102e308, v137
	v_fmamk_f32 v141, v140, 0x395133b1, v182
	v_cmp_eq_f32_e32 vcc, s94, v137
	v_cvt_i32_f32_e32 v137, v137
	v_fmaak_f32 v141, v140, v141, 0x3c0887f9
	v_fmaak_f32 v141, v140, v141, 0x3d2aaa81
	v_fmaak_f32 v141, v140, v141, 0x3e2aaaab
	v_fma_f32 v141, v140, v141, 0.5
	v_ldexp_f32 v137, 1.0, v137
	v_mul_f32_e32 v141, v140, v141
	v_cndmask_b32_e32 v137, v137, v193, vcc
	v_fmac_f32_e32 v140, v140, v141
	v_add_f32_e32 v141, -1.0, v137
	v_fmac_f32_e32 v141, v137, v140
	v_add_f32_e32 v137, v141, v141
	v_cndmask_b32_e32 v137, v141, v137, vcc
	v_cmp_nlt_f32_e32 vcc, s95, v139
	s_mov_b32 s16, 24
	s_nop 0
	v_cndmask_b32_e64 v137, v194, -v137, vcc
	v_cmp_ngt_f16_e32 vcc, s96, v138
	v_sub_f32_e32 v138, v134, v135
	v_mul_f32_e32 v138, 0x3fb8aa3b, v138
	v_exp_f32_e32 v138, v138
	v_cndmask_b32_e32 v137, 1.0, v137, vcc
	s_and_b64 vcc, exec, s[12:13]
	v_mul_f32_e32 v137, v138, v137
	v_bfe_u32 v138, v137, 16, 1
	v_add3_u32 v137, v137, v138, s33
	ds_write_b16_d16_hi v136, v137 offset:17408
	s_cbranch_vccnz .LBB0_649
	s_mov_b32 s16, 7
.LBB0_649:
	s_waitcnt vmcnt(21)
	v_mov_b32_e32 v138, v253
	v_cvt_f32_f16_e32 v139, v138
	v_lshlrev_b32_e32 v136, 16, v254
	s_cmp_lt_i32 s100, 0
	s_cbranch_scc1 .Lmy_hc_7
	ds_write_b16 v202, v255 offset:34830
.Lmy_hc_7:
	s_mul_i32 s101, s100, 15
	s_cmp_lt_i32 s100, 0
	s_cselect_b32 s30, 31, 0
	s_add_i32 s101, s101, s30
	s_lshl_b32 s30, s101, 10
	v_lshl_add_u64 v[132:133], v[130:131], 0, s[30:31]
	global_load_ushort v253, v[132:133], off
	s_mul_i32 s30, s101, 0x3b80
	v_lshl_add_u64 v[132:133], v[164:165], 0, s[30:31]
	global_load_ushort v254, v[132:133], off
	global_load_ushort v255, v[132:133], off offset:3072
	v_add_f32_e32 v135, v135, v139
	v_sub_f32_e32 v137, v135, v134
	v_mul_f32_e32 v137, 0x3fb8aa3b, v137
	v_exp_f32_e32 v137, v137
	s_nop 0
	v_mul_f32_e32 v136, v137, v136
	v_bfe_u32 v137, v136, 16, 1
	v_add3_u32 v140, v136, v137, s33
	v_or_b32_e32 v136, s16, v199
	v_mad_u64_u32 v[136:137], s[16:17], v136, s23, v[162:163]
	v_mul_f32_e32 v137, 0x3fb8aa3b, v139
	v_lshl_add_u32 v136, v136, 1, 16
	v_rndne_f32_e32 v137, v137
	ds_write_b16_d16_hi v136, v140
	v_fma_mix_f32 v140, v137, s97, v138 op_sel_hi:[0,0,1]
	v_fmac_f32_e32 v140, 0x3102e308, v137
	v_fmamk_f32 v141, v140, 0x395133b1, v182
	v_cmp_eq_f32_e32 vcc, s94, v137
	v_cvt_i32_f32_e32 v137, v137
	v_fmaak_f32 v141, v140, v141, 0x3c0887f9
	v_fmaak_f32 v141, v140, v141, 0x3d2aaa81
	v_fmaak_f32 v141, v140, v141, 0x3e2aaaab
	v_fma_f32 v141, v140, v141, 0.5
	v_ldexp_f32 v137, 1.0, v137
	v_mul_f32_e32 v141, v140, v141
	v_cndmask_b32_e32 v137, v137, v193, vcc
	v_fmac_f32_e32 v140, v140, v141
	v_add_f32_e32 v141, -1.0, v137
	v_fmac_f32_e32 v141, v137, v140
	v_add_f32_e32 v137, v141, v141
	v_cndmask_b32_e32 v137, v141, v137, vcc
	v_cmp_nlt_f32_e32 vcc, s95, v139
	s_mov_b32 s16, 23
	s_nop 0
	v_cndmask_b32_e64 v137, v194, -v137, vcc
	v_cmp_ngt_f16_e32 vcc, s96, v138
	v_sub_f32_e32 v138, v134, v135
	v_mul_f32_e32 v138, 0x3fb8aa3b, v138
	v_exp_f32_e32 v138, v138
	v_cndmask_b32_e32 v137, 1.0, v137, vcc
	s_and_b64 vcc, exec, s[12:13]
	v_mul_f32_e32 v137, v138, v137
	v_bfe_u32 v138, v137, 16, 1
	v_add3_u32 v137, v137, v138, s33
	ds_write_b16_d16_hi v136, v137 offset:17408
	s_cbranch_vccnz .LBB0_651
	s_mov_b32 s16, 8
.LBB0_651:
	s_waitcnt vmcnt(21)
	v_mov_b32_e32 v138, v232
	v_cvt_f32_f16_e32 v139, v138
	v_lshlrev_b32_e32 v136, 16, v233
	s_cmp_lt_i32 s100, 0
	s_cbranch_scc1 .Lmy_hc_8
	ds_write_b16 v202, v234 offset:34832
.Lmy_hc_8:
	s_mul_i32 s101, s100, 16
	s_cmp_lt_i32 s100, 0
	s_cselect_b32 s30, 31, 0
	s_add_i32 s101, s101, s30
	s_lshl_b32 s30, s101, 10
	v_lshl_add_u64 v[132:133], v[130:131], 0, s[30:31]
	global_load_ushort v232, v[132:133], off
	s_mul_i32 s30, s101, 0x3b80
	v_lshl_add_u64 v[132:133], v[164:165], 0, s[30:31]
	global_load_ushort v233, v[132:133], off
	global_load_ushort v234, v[132:133], off offset:3072
	v_add_f32_e32 v135, v135, v139
	v_sub_f32_e32 v137, v135, v134
	v_mul_f32_e32 v137, 0x3fb8aa3b, v137
	v_exp_f32_e32 v137, v137
	s_nop 0
	v_mul_f32_e32 v136, v137, v136
	v_bfe_u32 v137, v136, 16, 1
	v_add3_u32 v140, v136, v137, s33
	v_or_b32_e32 v136, s16, v199
	v_mad_u64_u32 v[136:137], s[16:17], v136, s23, v[162:163]
	v_mul_f32_e32 v137, 0x3fb8aa3b, v139
	v_lshl_add_u32 v136, v136, 1, 16
	v_rndne_f32_e32 v137, v137
	ds_write_b16_d16_hi v136, v140
	v_fma_mix_f32 v140, v137, s97, v138 op_sel_hi:[0,0,1]
	v_fmac_f32_e32 v140, 0x3102e308, v137
	v_fmamk_f32 v141, v140, 0x395133b1, v182
	v_cmp_eq_f32_e32 vcc, s94, v137
	v_cvt_i32_f32_e32 v137, v137
	v_fmaak_f32 v141, v140, v141, 0x3c0887f9
	v_fmaak_f32 v141, v140, v141, 0x3d2aaa81
	v_fmaak_f32 v141, v140, v141, 0x3e2aaaab
	v_fma_f32 v141, v140, v141, 0.5
	v_ldexp_f32 v137, 1.0, v137
	v_mul_f32_e32 v141, v140, v141
	v_cndmask_b32_e32 v137, v137, v193, vcc
	v_fmac_f32_e32 v140, v140, v141
	v_add_f32_e32 v141, -1.0, v137
	v_fmac_f32_e32 v141, v137, v140
	v_add_f32_e32 v137, v141, v141
	v_cndmask_b32_e32 v137, v141, v137, vcc
	v_cmp_nlt_f32_e32 vcc, s95, v139
	s_mov_b32 s16, 22
	s_nop 0
	v_cndmask_b32_e64 v137, v194, -v137, vcc
	v_cmp_ngt_f16_e32 vcc, s96, v138
	v_sub_f32_e32 v138, v134, v135
	v_mul_f32_e32 v138, 0x3fb8aa3b, v138
	v_exp_f32_e32 v138, v138
	v_cndmask_b32_e32 v137, 1.0, v137, vcc
	s_and_b64 vcc, exec, s[12:13]
	v_mul_f32_e32 v137, v138, v137
	v_bfe_u32 v138, v137, 16, 1
	v_add3_u32 v137, v137, v138, s33
	ds_write_b16_d16_hi v136, v137 offset:17408
	s_cbranch_vccnz .LBB0_653
	s_mov_b32 s16, 9
.LBB0_653:
	s_waitcnt vmcnt(21)
	v_mov_b32_e32 v138, v235
	v_cvt_f32_f16_e32 v139, v138
	v_lshlrev_b32_e32 v136, 16, v236
	s_cmp_lt_i32 s100, 0
	s_cbranch_scc1 .Lmy_hc_9
	ds_write_b16 v202, v237 offset:34834
.Lmy_hc_9:
	s_mul_i32 s101, s100, 17
	s_cmp_lt_i32 s100, 0
	s_cselect_b32 s30, 31, 0
	s_add_i32 s101, s101, s30
	s_lshl_b32 s30, s101, 10
	v_lshl_add_u64 v[132:133], v[130:131], 0, s[30:31]
	global_load_ushort v235, v[132:133], off
	s_mul_i32 s30, s101, 0x3b80
	v_lshl_add_u64 v[132:133], v[164:165], 0, s[30:31]
	global_load_ushort v236, v[132:133], off
	global_load_ushort v237, v[132:133], off offset:3072
	v_add_f32_e32 v135, v135, v139
	v_sub_f32_e32 v137, v135, v134
	v_mul_f32_e32 v137, 0x3fb8aa3b, v137
	v_exp_f32_e32 v137, v137
	s_nop 0
	v_mul_f32_e32 v136, v137, v136
	v_bfe_u32 v137, v136, 16, 1
	v_add3_u32 v140, v136, v137, s33
	v_or_b32_e32 v136, s16, v199
	v_mad_u64_u32 v[136:137], s[16:17], v136, s23, v[162:163]
	v_mul_f32_e32 v137, 0x3fb8aa3b, v139
	v_lshl_add_u32 v136, v136, 1, 16
	v_rndne_f32_e32 v137, v137
	ds_write_b16_d16_hi v136, v140
	v_fma_mix_f32 v140, v137, s97, v138 op_sel_hi:[0,0,1]
	v_fmac_f32_e32 v140, 0x3102e308, v137
	v_fmamk_f32 v141, v140, 0x395133b1, v182
	v_cmp_eq_f32_e32 vcc, s94, v137
	v_cvt_i32_f32_e32 v137, v137
	v_fmaak_f32 v141, v140, v141, 0x3c0887f9
	v_fmaak_f32 v141, v140, v141, 0x3d2aaa81
	v_fmaak_f32 v141, v140, v141, 0x3e2aaaab
	v_fma_f32 v141, v140, v141, 0.5
	v_ldexp_f32 v137, 1.0, v137
	v_mul_f32_e32 v141, v140, v141
	v_cndmask_b32_e32 v137, v137, v193, vcc
	v_fmac_f32_e32 v140, v140, v141
	v_add_f32_e32 v141, -1.0, v137
	v_fmac_f32_e32 v141, v137, v140
	v_add_f32_e32 v137, v141, v141
	v_cndmask_b32_e32 v137, v141, v137, vcc
	v_cmp_nlt_f32_e32 vcc, s95, v139
	s_mov_b32 s16, 21
	s_nop 0
	v_cndmask_b32_e64 v137, v194, -v137, vcc
	v_cmp_ngt_f16_e32 vcc, s96, v138
	v_sub_f32_e32 v138, v134, v135
	v_mul_f32_e32 v138, 0x3fb8aa3b, v138
	v_exp_f32_e32 v138, v138
	v_cndmask_b32_e32 v137, 1.0, v137, vcc
	s_and_b64 vcc, exec, s[12:13]
	v_mul_f32_e32 v137, v138, v137
	v_bfe_u32 v138, v137, 16, 1
	v_add3_u32 v137, v137, v138, s33
	ds_write_b16_d16_hi v136, v137 offset:17408
	s_cbranch_vccnz .LBB0_655
	s_mov_b32 s16, 10
.LBB0_655:
	s_waitcnt vmcnt(21)
	v_mov_b32_e32 v138, v238
	v_cvt_f32_f16_e32 v139, v138
	v_lshlrev_b32_e32 v136, 16, v239
	s_cmp_lt_i32 s100, 0
	s_cbranch_scc1 .Lmy_hc_10
	ds_write_b16 v202, v240 offset:34836
.Lmy_hc_10:
	s_mul_i32 s101, s100, 18
	s_cmp_lt_i32 s100, 0
	s_cselect_b32 s30, 31, 0
	s_add_i32 s101, s101, s30
	s_lshl_b32 s30, s101, 10
	v_lshl_add_u64 v[132:133], v[130:131], 0, s[30:31]
	global_load_ushort v238, v[132:133], off
	s_mul_i32 s30, s101, 0x3b80
	v_lshl_add_u64 v[132:133], v[164:165], 0, s[30:31]
	global_load_ushort v239, v[132:133], off
	global_load_ushort v240, v[132:133], off offset:3072
	v_add_f32_e32 v135, v135, v139
	v_sub_f32_e32 v137, v135, v134
	v_mul_f32_e32 v137, 0x3fb8aa3b, v137
	v_exp_f32_e32 v137, v137
	s_nop 0
	v_mul_f32_e32 v136, v137, v136
	v_bfe_u32 v137, v136, 16, 1
	v_add3_u32 v140, v136, v137, s33
	v_or_b32_e32 v136, s16, v199
	v_mad_u64_u32 v[136:137], s[16:17], v136, s23, v[162:163]
	v_mul_f32_e32 v137, 0x3fb8aa3b, v139
	v_lshl_add_u32 v136, v136, 1, 16
	v_rndne_f32_e32 v137, v137
	ds_write_b16_d16_hi v136, v140
	v_fma_mix_f32 v140, v137, s97, v138 op_sel_hi:[0,0,1]
	v_fmac_f32_e32 v140, 0x3102e308, v137
	v_fmamk_f32 v141, v140, 0x395133b1, v182
	v_cmp_eq_f32_e32 vcc, s94, v137
	v_cvt_i32_f32_e32 v137, v137
	v_fmaak_f32 v141, v140, v141, 0x3c0887f9
	v_fmaak_f32 v141, v140, v141, 0x3d2aaa81
	v_fmaak_f32 v141, v140, v141, 0x3e2aaaab
	v_fma_f32 v141, v140, v141, 0.5
	v_ldexp_f32 v137, 1.0, v137
	v_mul_f32_e32 v141, v140, v141
	v_cndmask_b32_e32 v137, v137, v193, vcc
	v_fmac_f32_e32 v140, v140, v141
	v_add_f32_e32 v141, -1.0, v137
	v_fmac_f32_e32 v141, v137, v140
	v_add_f32_e32 v137, v141, v141
	v_cndmask_b32_e32 v137, v141, v137, vcc
	v_cmp_nlt_f32_e32 vcc, s95, v139
	s_mov_b32 s16, 20
	s_nop 0
	v_cndmask_b32_e64 v137, v194, -v137, vcc
	v_cmp_ngt_f16_e32 vcc, s96, v138
	v_sub_f32_e32 v138, v134, v135
	v_mul_f32_e32 v138, 0x3fb8aa3b, v138
	v_exp_f32_e32 v138, v138
	v_cndmask_b32_e32 v137, 1.0, v137, vcc
	s_and_b64 vcc, exec, s[12:13]
	v_mul_f32_e32 v137, v138, v137
	v_bfe_u32 v138, v137, 16, 1
	v_add3_u32 v137, v137, v138, s33
	ds_write_b16_d16_hi v136, v137 offset:17408
	s_cbranch_vccnz .LBB0_657
	s_mov_b32 s16, 11
.LBB0_657:
	s_waitcnt vmcnt(21)
	v_mov_b32_e32 v138, v241
	v_cvt_f32_f16_e32 v139, v138
	v_lshlrev_b32_e32 v136, 16, v242
	s_cmp_lt_i32 s100, 0
	s_cbranch_scc1 .Lmy_hc_11
	ds_write_b16 v202, v243 offset:34838
.Lmy_hc_11:
	s_mul_i32 s101, s100, 19
	s_cmp_lt_i32 s100, 0
	s_cselect_b32 s30, 31, 0
	s_add_i32 s101, s101, s30
	s_lshl_b32 s30, s101, 10
	v_lshl_add_u64 v[132:133], v[130:131], 0, s[30:31]
	global_load_ushort v241, v[132:133], off
	s_mul_i32 s30, s101, 0x3b80
	v_lshl_add_u64 v[132:133], v[164:165], 0, s[30:31]
	global_load_ushort v242, v[132:133], off
	global_load_ushort v243, v[132:133], off offset:3072
	v_add_f32_e32 v135, v135, v139
	v_sub_f32_e32 v137, v135, v134
	v_mul_f32_e32 v137, 0x3fb8aa3b, v137
	v_exp_f32_e32 v137, v137
	s_nop 0
	v_mul_f32_e32 v136, v137, v136
	v_bfe_u32 v137, v136, 16, 1
	v_add3_u32 v140, v136, v137, s33
	v_or_b32_e32 v136, s16, v199
	v_mad_u64_u32 v[136:137], s[16:17], v136, s23, v[162:163]
	v_mul_f32_e32 v137, 0x3fb8aa3b, v139
	v_lshl_add_u32 v136, v136, 1, 16
	v_rndne_f32_e32 v137, v137
	ds_write_b16_d16_hi v136, v140
	v_fma_mix_f32 v140, v137, s97, v138 op_sel_hi:[0,0,1]
	v_fmac_f32_e32 v140, 0x3102e308, v137
	v_fmamk_f32 v141, v140, 0x395133b1, v182
	v_cmp_eq_f32_e32 vcc, s94, v137
	v_cvt_i32_f32_e32 v137, v137
	v_fmaak_f32 v141, v140, v141, 0x3c0887f9
	v_fmaak_f32 v141, v140, v141, 0x3d2aaa81
	v_fmaak_f32 v141, v140, v141, 0x3e2aaaab
	v_fma_f32 v141, v140, v141, 0.5
	v_ldexp_f32 v137, 1.0, v137
	v_mul_f32_e32 v141, v140, v141
	v_cndmask_b32_e32 v137, v137, v193, vcc
	v_fmac_f32_e32 v140, v140, v141
	v_add_f32_e32 v141, -1.0, v137
	v_fmac_f32_e32 v141, v137, v140
	v_add_f32_e32 v137, v141, v141
	v_cndmask_b32_e32 v137, v141, v137, vcc
	v_cmp_nlt_f32_e32 vcc, s95, v139
	s_mov_b32 s16, 19
	s_nop 0
	v_cndmask_b32_e64 v137, v194, -v137, vcc
	v_cmp_ngt_f16_e32 vcc, s96, v138
	v_sub_f32_e32 v138, v134, v135
	v_mul_f32_e32 v138, 0x3fb8aa3b, v138
	v_exp_f32_e32 v138, v138
	v_cndmask_b32_e32 v137, 1.0, v137, vcc
	s_and_b64 vcc, exec, s[12:13]
	v_mul_f32_e32 v137, v138, v137
	v_bfe_u32 v138, v137, 16, 1
	v_add3_u32 v137, v137, v138, s33
	ds_write_b16_d16_hi v136, v137 offset:17408
	s_cbranch_vccnz .LBB0_659
	s_mov_b32 s16, 12
.LBB0_659:
	s_waitcnt vmcnt(21)
	v_mov_b32_e32 v138, v244
	v_cvt_f32_f16_e32 v139, v138
	v_lshlrev_b32_e32 v136, 16, v245
	s_cmp_lt_i32 s100, 0
	s_cbranch_scc1 .Lmy_hc_12
	ds_write_b16 v202, v246 offset:34840
.Lmy_hc_12:
	s_mul_i32 s101, s100, 20
	s_cmp_lt_i32 s100, 0
	s_cselect_b32 s30, 31, 0
	s_add_i32 s101, s101, s30
	s_lshl_b32 s30, s101, 10
	v_lshl_add_u64 v[132:133], v[130:131], 0, s[30:31]
	global_load_ushort v244, v[132:133], off
	s_mul_i32 s30, s101, 0x3b80
	v_lshl_add_u64 v[132:133], v[164:165], 0, s[30:31]
	global_load_ushort v245, v[132:133], off
	global_load_ushort v246, v[132:133], off offset:3072
	v_add_f32_e32 v135, v135, v139
	v_sub_f32_e32 v137, v135, v134
	v_mul_f32_e32 v137, 0x3fb8aa3b, v137
	v_exp_f32_e32 v137, v137
	s_nop 0
	v_mul_f32_e32 v136, v137, v136
	v_bfe_u32 v137, v136, 16, 1
	v_add3_u32 v140, v136, v137, s33
	v_or_b32_e32 v136, s16, v199
	v_mad_u64_u32 v[136:137], s[16:17], v136, s23, v[162:163]
	v_mul_f32_e32 v137, 0x3fb8aa3b, v139
	v_lshl_add_u32 v136, v136, 1, 16
	v_rndne_f32_e32 v137, v137
	ds_write_b16_d16_hi v136, v140
	v_fma_mix_f32 v140, v137, s97, v138 op_sel_hi:[0,0,1]
	v_fmac_f32_e32 v140, 0x3102e308, v137
	v_fmamk_f32 v141, v140, 0x395133b1, v182
	v_cmp_eq_f32_e32 vcc, s94, v137
	v_cvt_i32_f32_e32 v137, v137
	v_fmaak_f32 v141, v140, v141, 0x3c0887f9
	v_fmaak_f32 v141, v140, v141, 0x3d2aaa81
	v_fmaak_f32 v141, v140, v141, 0x3e2aaaab
	v_fma_f32 v141, v140, v141, 0.5
	v_ldexp_f32 v137, 1.0, v137
	v_mul_f32_e32 v141, v140, v141
	v_cndmask_b32_e32 v137, v137, v193, vcc
	v_fmac_f32_e32 v140, v140, v141
	v_add_f32_e32 v141, -1.0, v137
	v_fmac_f32_e32 v141, v137, v140
	v_add_f32_e32 v137, v141, v141
	v_cndmask_b32_e32 v137, v141, v137, vcc
	v_cmp_nlt_f32_e32 vcc, s95, v139
	s_mov_b32 s16, 18
	s_nop 0
	v_cndmask_b32_e64 v137, v194, -v137, vcc
	v_cmp_ngt_f16_e32 vcc, s96, v138
	v_sub_f32_e32 v138, v134, v135
	v_mul_f32_e32 v138, 0x3fb8aa3b, v138
	v_exp_f32_e32 v138, v138
	v_cndmask_b32_e32 v137, 1.0, v137, vcc
	s_and_b64 vcc, exec, s[12:13]
	v_mul_f32_e32 v137, v138, v137
	v_bfe_u32 v138, v137, 16, 1
	v_add3_u32 v137, v137, v138, s33
	ds_write_b16_d16_hi v136, v137 offset:17408
	s_cbranch_vccnz .LBB0_661
	s_mov_b32 s16, 13
.LBB0_661:
	s_waitcnt vmcnt(21)
	v_mov_b32_e32 v138, v247
	v_cvt_f32_f16_e32 v139, v138
	v_lshlrev_b32_e32 v136, 16, v248
	s_cmp_lt_i32 s100, 0
	s_cbranch_scc1 .Lmy_hc_13
	ds_write_b16 v202, v249 offset:34842
.Lmy_hc_13:
	s_mul_i32 s101, s100, 21
	s_cmp_lt_i32 s100, 0
	s_cselect_b32 s30, 31, 0
	s_add_i32 s101, s101, s30
	s_lshl_b32 s30, s101, 10
	v_lshl_add_u64 v[132:133], v[130:131], 0, s[30:31]
	global_load_ushort v247, v[132:133], off
	s_mul_i32 s30, s101, 0x3b80
	v_lshl_add_u64 v[132:133], v[164:165], 0, s[30:31]
	global_load_ushort v248, v[132:133], off
	global_load_ushort v249, v[132:133], off offset:3072
	v_add_f32_e32 v135, v135, v139
	v_sub_f32_e32 v137, v135, v134
	v_mul_f32_e32 v137, 0x3fb8aa3b, v137
	v_exp_f32_e32 v137, v137
	s_nop 0
	v_mul_f32_e32 v136, v137, v136
	v_bfe_u32 v137, v136, 16, 1
	v_add3_u32 v140, v136, v137, s33
	v_or_b32_e32 v136, s16, v199
	v_mad_u64_u32 v[136:137], s[16:17], v136, s23, v[162:163]
	v_mul_f32_e32 v137, 0x3fb8aa3b, v139
	v_lshl_add_u32 v136, v136, 1, 16
	v_rndne_f32_e32 v137, v137
	ds_write_b16_d16_hi v136, v140
	v_fma_mix_f32 v140, v137, s97, v138 op_sel_hi:[0,0,1]
	v_fmac_f32_e32 v140, 0x3102e308, v137
	v_fmamk_f32 v141, v140, 0x395133b1, v182
	v_cmp_eq_f32_e32 vcc, s94, v137
	v_cvt_i32_f32_e32 v137, v137
	v_fmaak_f32 v141, v140, v141, 0x3c0887f9
	v_fmaak_f32 v141, v140, v141, 0x3d2aaa81
	v_fmaak_f32 v141, v140, v141, 0x3e2aaaab
	v_fma_f32 v141, v140, v141, 0.5
	v_ldexp_f32 v137, 1.0, v137
	v_mul_f32_e32 v141, v140, v141
	v_cndmask_b32_e32 v137, v137, v193, vcc
	v_fmac_f32_e32 v140, v140, v141
	v_add_f32_e32 v141, -1.0, v137
	v_fmac_f32_e32 v141, v137, v140
	v_add_f32_e32 v137, v141, v141
	v_cndmask_b32_e32 v137, v141, v137, vcc
	v_cmp_nlt_f32_e32 vcc, s95, v139
	s_mov_b32 s16, 17
	s_nop 0
	v_cndmask_b32_e64 v137, v194, -v137, vcc
	v_cmp_ngt_f16_e32 vcc, s96, v138
	v_sub_f32_e32 v138, v134, v135
	v_mul_f32_e32 v138, 0x3fb8aa3b, v138
	v_exp_f32_e32 v138, v138
	v_cndmask_b32_e32 v137, 1.0, v137, vcc
	s_and_b64 vcc, exec, s[12:13]
	v_mul_f32_e32 v137, v138, v137
	v_bfe_u32 v138, v137, 16, 1
	v_add3_u32 v137, v137, v138, s33
	ds_write_b16_d16_hi v136, v137 offset:17408
	s_cbranch_vccnz .LBB0_663
	s_mov_b32 s16, 14
.LBB0_663:
	s_waitcnt vmcnt(21)
	v_mov_b32_e32 v138, v250
	s_mov_b32 s17, 16
	v_cvt_f32_f16_e32 v139, v138
	v_lshlrev_b32_e32 v136, 16, v251
	s_cmp_lt_i32 s100, 0
	s_cbranch_scc1 .Lmy_hc_14
	ds_write_b16 v202, v252 offset:34844
.Lmy_hc_14:
	s_mul_i32 s101, s100, 22
	s_cmp_lt_i32 s100, 0
	s_cselect_b32 s30, 31, 0
	s_add_i32 s101, s101, s30
	s_lshl_b32 s30, s101, 10
	v_lshl_add_u64 v[132:133], v[130:131], 0, s[30:31]
	global_load_ushort v250, v[132:133], off
	s_mul_i32 s30, s101, 0x3b80
	v_lshl_add_u64 v[132:133], v[164:165], 0, s[30:31]
	global_load_ushort v251, v[132:133], off
	global_load_ushort v252, v[132:133], off offset:3072
	v_add_f32_e32 v135, v135, v139
	v_sub_f32_e32 v137, v135, v134
	v_mul_f32_e32 v137, 0x3fb8aa3b, v137
	v_exp_f32_e32 v137, v137
	s_nop 0
	v_mul_f32_e32 v136, v137, v136
	v_bfe_u32 v137, v136, 16, 1
	v_add3_u32 v140, v136, v137, s33
	v_or_b32_e32 v136, s16, v199
	v_mad_u64_u32 v[136:137], s[18:19], v136, s23, v[162:163]
	v_mul_f32_e32 v137, 0x3fb8aa3b, v139
	v_lshl_add_u32 v136, v136, 1, 16
	v_rndne_f32_e32 v137, v137
	ds_write_b16_d16_hi v136, v140
	v_fma_mix_f32 v140, v137, s97, v138 op_sel_hi:[0,0,1]
	v_fmac_f32_e32 v140, 0x3102e308, v137
	v_fmamk_f32 v141, v140, 0x395133b1, v182
	v_cmp_eq_f32_e32 vcc, s94, v137
	v_cvt_i32_f32_e32 v137, v137
	v_fmaak_f32 v141, v140, v141, 0x3c0887f9
	v_fmaak_f32 v141, v140, v141, 0x3d2aaa81
	v_fmaak_f32 v141, v140, v141, 0x3e2aaaab
	v_fma_f32 v141, v140, v141, 0.5
	v_ldexp_f32 v137, 1.0, v137
	v_mul_f32_e32 v141, v140, v141
	v_cndmask_b32_e32 v137, v137, v193, vcc
	v_fmac_f32_e32 v140, v140, v141
	v_add_f32_e32 v141, -1.0, v137
	v_fmac_f32_e32 v141, v137, v140
	v_add_f32_e32 v137, v141, v141
	v_cndmask_b32_e32 v137, v141, v137, vcc
	v_cmp_nlt_f32_e32 vcc, s95, v139
	s_nop 1
	v_cndmask_b32_e64 v137, v194, -v137, vcc
	v_cmp_ngt_f16_e32 vcc, s96, v138
	v_sub_f32_e32 v138, v134, v135
	v_mul_f32_e32 v138, 0x3fb8aa3b, v138
	v_exp_f32_e32 v138, v138
	v_cndmask_b32_e32 v137, 1.0, v137, vcc
	s_and_b64 vcc, exec, s[12:13]
	v_mul_f32_e32 v137, v138, v137
	v_bfe_u32 v138, v137, 16, 1
	v_add3_u32 v137, v137, v138, s33
	ds_write_b16_d16_hi v136, v137 offset:17408
	s_cbranch_vccnz .LBB0_665
	s_mov_b32 s17, 15
.LBB0_665:
	s_waitcnt vmcnt(21)
	v_mov_b32_e32 v138, v253
	v_cvt_f32_f16_e32 v139, v138
	v_lshlrev_b32_e32 v136, 16, v254
	s_cmp_lt_i32 s100, 0
	s_cbranch_scc1 .Lmy_hc_15
	ds_write_b16 v202, v255 offset:34846
.Lmy_hc_15:
	s_mul_i32 s101, s100, 23
	s_cmp_lt_i32 s100, 0
	s_cselect_b32 s30, 31, 0
	s_add_i32 s101, s101, s30
	s_lshl_b32 s30, s101, 10
	v_lshl_add_u64 v[132:133], v[130:131], 0, s[30:31]
	global_load_ushort v253, v[132:133], off
	s_mul_i32 s30, s101, 0x3b80
	v_lshl_add_u64 v[132:133], v[164:165], 0, s[30:31]
	global_load_ushort v254, v[132:133], off
	global_load_ushort v255, v[132:133], off offset:3072
	v_add_f32_e32 v135, v135, v139
	v_sub_f32_e32 v137, v135, v134
	v_mul_f32_e32 v137, 0x3fb8aa3b, v137
	v_exp_f32_e32 v137, v137
	s_nop 0
	v_mul_f32_e32 v136, v137, v136
	v_bfe_u32 v137, v136, 16, 1
	v_add3_u32 v140, v136, v137, s33
	v_or_b32_e32 v136, s17, v199
	v_mad_u64_u32 v[136:137], s[16:17], v136, s23, v[162:163]
	v_mul_f32_e32 v137, 0x3fb8aa3b, v139
	v_lshl_add_u32 v136, v136, 1, 16
	v_rndne_f32_e32 v137, v137
	ds_write_b16_d16_hi v136, v140
	v_fma_mix_f32 v140, v137, s97, v138 op_sel_hi:[0,0,1]
	v_fmac_f32_e32 v140, 0x3102e308, v137
	v_fmamk_f32 v141, v140, 0x395133b1, v182
	v_cmp_eq_f32_e32 vcc, s94, v137
	v_cvt_i32_f32_e32 v137, v137
	v_fmaak_f32 v141, v140, v141, 0x3c0887f9
	v_fmaak_f32 v141, v140, v141, 0x3d2aaa81
	v_fmaak_f32 v141, v140, v141, 0x3e2aaaab
	v_fma_f32 v141, v140, v141, 0.5
	v_ldexp_f32 v137, 1.0, v137
	v_mul_f32_e32 v141, v140, v141
	v_cndmask_b32_e32 v137, v137, v193, vcc
	v_fmac_f32_e32 v140, v140, v141
	v_add_f32_e32 v141, -1.0, v137
	v_fmac_f32_e32 v141, v137, v140
	v_add_f32_e32 v137, v141, v141
	v_cndmask_b32_e32 v137, v141, v137, vcc
	v_cmp_nlt_f32_e32 vcc, s95, v139
	s_mov_b32 s16, 15
	s_nop 0
	v_cndmask_b32_e64 v137, v194, -v137, vcc
	v_cmp_ngt_f16_e32 vcc, s96, v138
	v_sub_f32_e32 v138, v134, v135
	v_mul_f32_e32 v138, 0x3fb8aa3b, v138
	v_exp_f32_e32 v138, v138
	v_cndmask_b32_e32 v137, 1.0, v137, vcc
	s_and_b64 vcc, exec, s[12:13]
	v_mul_f32_e32 v137, v138, v137
	v_bfe_u32 v138, v137, 16, 1
	v_add3_u32 v137, v137, v138, s33
	ds_write_b16_d16_hi v136, v137 offset:17408
	s_cbranch_vccnz .LBB0_667
	s_mov_b32 s16, 16
.LBB0_667:
	s_waitcnt vmcnt(21)
	v_mov_b32_e32 v138, v232
	v_cvt_f32_f16_e32 v139, v138
	v_lshlrev_b32_e32 v136, 16, v233
	s_cmp_lt_i32 s100, 0
	s_cbranch_scc1 .Lmy_hc_16
	ds_write_b16 v202, v234 offset:34848
.Lmy_hc_16:
	s_mul_i32 s101, s100, 24
	s_cmp_lt_i32 s100, 0
	s_cselect_b32 s30, 31, 0
	s_add_i32 s101, s101, s30
	s_lshl_b32 s30, s101, 10
	v_lshl_add_u64 v[132:133], v[130:131], 0, s[30:31]
	global_load_ushort v232, v[132:133], off
	s_mul_i32 s30, s101, 0x3b80
	v_lshl_add_u64 v[132:133], v[164:165], 0, s[30:31]
	global_load_ushort v233, v[132:133], off
	global_load_ushort v234, v[132:133], off offset:3072
	v_add_f32_e32 v135, v135, v139
	v_sub_f32_e32 v137, v135, v134
	v_mul_f32_e32 v137, 0x3fb8aa3b, v137
	v_exp_f32_e32 v137, v137
	s_nop 0
	v_mul_f32_e32 v136, v137, v136
	v_bfe_u32 v137, v136, 16, 1
	v_add3_u32 v140, v136, v137, s33
	v_or_b32_e32 v136, s16, v199
	v_mad_u64_u32 v[136:137], s[16:17], v136, s23, v[162:163]
	v_mul_f32_e32 v137, 0x3fb8aa3b, v139
	v_lshl_add_u32 v136, v136, 1, 16
	v_rndne_f32_e32 v137, v137
	ds_write_b16_d16_hi v136, v140
	v_fma_mix_f32 v140, v137, s97, v138 op_sel_hi:[0,0,1]
	v_fmac_f32_e32 v140, 0x3102e308, v137
	v_fmamk_f32 v141, v140, 0x395133b1, v182
	v_cmp_eq_f32_e32 vcc, s94, v137
	v_cvt_i32_f32_e32 v137, v137
	v_fmaak_f32 v141, v140, v141, 0x3c0887f9
	v_fmaak_f32 v141, v140, v141, 0x3d2aaa81
	v_fmaak_f32 v141, v140, v141, 0x3e2aaaab
	v_fma_f32 v141, v140, v141, 0.5
	v_ldexp_f32 v137, 1.0, v137
	v_mul_f32_e32 v141, v140, v141
	v_cndmask_b32_e32 v137, v137, v193, vcc
	v_fmac_f32_e32 v140, v140, v141
	v_add_f32_e32 v141, -1.0, v137
	v_fmac_f32_e32 v141, v137, v140
	v_add_f32_e32 v137, v141, v141
	v_cndmask_b32_e32 v137, v141, v137, vcc
	v_cmp_nlt_f32_e32 vcc, s95, v139
	s_mov_b32 s16, 14
	s_nop 0
	v_cndmask_b32_e64 v137, v194, -v137, vcc
	v_cmp_ngt_f16_e32 vcc, s96, v138
	v_sub_f32_e32 v138, v134, v135
	v_mul_f32_e32 v138, 0x3fb8aa3b, v138
	v_exp_f32_e32 v138, v138
	v_cndmask_b32_e32 v137, 1.0, v137, vcc
	s_and_b64 vcc, exec, s[12:13]
	v_mul_f32_e32 v137, v138, v137
	v_bfe_u32 v138, v137, 16, 1
	v_add3_u32 v137, v137, v138, s33
	ds_write_b16_d16_hi v136, v137 offset:17408
	s_cbranch_vccnz .LBB0_669
	s_mov_b32 s16, 17
.LBB0_669:
	s_waitcnt vmcnt(21)
	v_mov_b32_e32 v138, v235
	v_cvt_f32_f16_e32 v139, v138
	v_lshlrev_b32_e32 v136, 16, v236
	s_cmp_lt_i32 s100, 0
	s_cbranch_scc1 .Lmy_hc_17
	ds_write_b16 v202, v237 offset:34850
.Lmy_hc_17:
	s_mul_i32 s101, s100, 25
	s_cmp_lt_i32 s100, 0
	s_cselect_b32 s30, 31, 0
	s_add_i32 s101, s101, s30
	s_lshl_b32 s30, s101, 10
	v_lshl_add_u64 v[132:133], v[130:131], 0, s[30:31]
	global_load_ushort v235, v[132:133], off
	s_mul_i32 s30, s101, 0x3b80
	v_lshl_add_u64 v[132:133], v[164:165], 0, s[30:31]
	global_load_ushort v236, v[132:133], off
	global_load_ushort v237, v[132:133], off offset:3072
	v_add_f32_e32 v135, v135, v139
	v_sub_f32_e32 v137, v135, v134
	v_mul_f32_e32 v137, 0x3fb8aa3b, v137
	v_exp_f32_e32 v137, v137
	s_nop 0
	v_mul_f32_e32 v136, v137, v136
	v_bfe_u32 v137, v136, 16, 1
	v_add3_u32 v140, v136, v137, s33
	v_or_b32_e32 v136, s16, v199
	v_mad_u64_u32 v[136:137], s[16:17], v136, s23, v[162:163]
	v_mul_f32_e32 v137, 0x3fb8aa3b, v139
	v_lshl_add_u32 v136, v136, 1, 16
	v_rndne_f32_e32 v137, v137
	ds_write_b16_d16_hi v136, v140
	v_fma_mix_f32 v140, v137, s97, v138 op_sel_hi:[0,0,1]
	v_fmac_f32_e32 v140, 0x3102e308, v137
	v_fmamk_f32 v141, v140, 0x395133b1, v182
	v_cmp_eq_f32_e32 vcc, s94, v137
	v_cvt_i32_f32_e32 v137, v137
	v_fmaak_f32 v141, v140, v141, 0x3c0887f9
	v_fmaak_f32 v141, v140, v141, 0x3d2aaa81
	v_fmaak_f32 v141, v140, v141, 0x3e2aaaab
	v_fma_f32 v141, v140, v141, 0.5
	v_ldexp_f32 v137, 1.0, v137
	v_mul_f32_e32 v141, v140, v141
	v_cndmask_b32_e32 v137, v137, v193, vcc
	v_fmac_f32_e32 v140, v140, v141
	v_add_f32_e32 v141, -1.0, v137
	v_fmac_f32_e32 v141, v137, v140
	v_add_f32_e32 v137, v141, v141
	v_cndmask_b32_e32 v137, v141, v137, vcc
	v_cmp_nlt_f32_e32 vcc, s95, v139
	s_mov_b32 s16, 13
	s_nop 0
	v_cndmask_b32_e64 v137, v194, -v137, vcc
	v_cmp_ngt_f16_e32 vcc, s96, v138
	v_sub_f32_e32 v138, v134, v135
	v_mul_f32_e32 v138, 0x3fb8aa3b, v138
	v_exp_f32_e32 v138, v138
	v_cndmask_b32_e32 v137, 1.0, v137, vcc
	s_and_b64 vcc, exec, s[12:13]
	v_mul_f32_e32 v137, v138, v137
	v_bfe_u32 v138, v137, 16, 1
	v_add3_u32 v137, v137, v138, s33
	ds_write_b16_d16_hi v136, v137 offset:17408
	s_cbranch_vccnz .LBB0_671
	s_mov_b32 s16, 18
.LBB0_671:
	s_waitcnt vmcnt(21)
	v_mov_b32_e32 v138, v238
	v_cvt_f32_f16_e32 v139, v138
	v_lshlrev_b32_e32 v136, 16, v239
	s_cmp_lt_i32 s100, 0
	s_cbranch_scc1 .Lmy_hc_18
	ds_write_b16 v202, v240 offset:34852
.Lmy_hc_18:
	s_mul_i32 s101, s100, 26
	s_cmp_lt_i32 s100, 0
	s_cselect_b32 s30, 31, 0
	s_add_i32 s101, s101, s30
	s_lshl_b32 s30, s101, 10
	v_lshl_add_u64 v[132:133], v[130:131], 0, s[30:31]
	global_load_ushort v238, v[132:133], off
	s_mul_i32 s30, s101, 0x3b80
	v_lshl_add_u64 v[132:133], v[164:165], 0, s[30:31]
	global_load_ushort v239, v[132:133], off
	global_load_ushort v240, v[132:133], off offset:3072
	v_add_f32_e32 v135, v135, v139
	v_sub_f32_e32 v137, v135, v134
	v_mul_f32_e32 v137, 0x3fb8aa3b, v137
	v_exp_f32_e32 v137, v137
	s_nop 0
	v_mul_f32_e32 v136, v137, v136
	v_bfe_u32 v137, v136, 16, 1
	v_add3_u32 v140, v136, v137, s33
	v_or_b32_e32 v136, s16, v199
	v_mad_u64_u32 v[136:137], s[16:17], v136, s23, v[162:163]
	v_mul_f32_e32 v137, 0x3fb8aa3b, v139
	v_lshl_add_u32 v136, v136, 1, 16
	v_rndne_f32_e32 v137, v137
	ds_write_b16_d16_hi v136, v140
	v_fma_mix_f32 v140, v137, s97, v138 op_sel_hi:[0,0,1]
	v_fmac_f32_e32 v140, 0x3102e308, v137
	v_fmamk_f32 v141, v140, 0x395133b1, v182
	v_cmp_eq_f32_e32 vcc, s94, v137
	v_cvt_i32_f32_e32 v137, v137
	v_fmaak_f32 v141, v140, v141, 0x3c0887f9
	v_fmaak_f32 v141, v140, v141, 0x3d2aaa81
	v_fmaak_f32 v141, v140, v141, 0x3e2aaaab
	v_fma_f32 v141, v140, v141, 0.5
	v_ldexp_f32 v137, 1.0, v137
	v_mul_f32_e32 v141, v140, v141
	v_cndmask_b32_e32 v137, v137, v193, vcc
	v_fmac_f32_e32 v140, v140, v141
	v_add_f32_e32 v141, -1.0, v137
	v_fmac_f32_e32 v141, v137, v140
	v_add_f32_e32 v137, v141, v141
	v_cndmask_b32_e32 v137, v141, v137, vcc
	v_cmp_nlt_f32_e32 vcc, s95, v139
	s_mov_b32 s16, 12
	s_nop 0
	v_cndmask_b32_e64 v137, v194, -v137, vcc
	v_cmp_ngt_f16_e32 vcc, s96, v138
	v_sub_f32_e32 v138, v134, v135
	v_mul_f32_e32 v138, 0x3fb8aa3b, v138
	v_exp_f32_e32 v138, v138
	v_cndmask_b32_e32 v137, 1.0, v137, vcc
	s_and_b64 vcc, exec, s[12:13]
	v_mul_f32_e32 v137, v138, v137
	v_bfe_u32 v138, v137, 16, 1
	v_add3_u32 v137, v137, v138, s33
	ds_write_b16_d16_hi v136, v137 offset:17408
	s_cbranch_vccnz .LBB0_673
	s_mov_b32 s16, 19
.LBB0_673:
	s_waitcnt vmcnt(21)
	v_mov_b32_e32 v138, v241
	v_cvt_f32_f16_e32 v139, v138
	v_lshlrev_b32_e32 v136, 16, v242
	s_cmp_lt_i32 s100, 0
	s_cbranch_scc1 .Lmy_hc_19
	ds_write_b16 v202, v243 offset:34854
.Lmy_hc_19:
	s_mul_i32 s101, s100, 27
	s_cmp_lt_i32 s100, 0
	s_cselect_b32 s30, 31, 0
	s_add_i32 s101, s101, s30
	s_lshl_b32 s30, s101, 10
	v_lshl_add_u64 v[132:133], v[130:131], 0, s[30:31]
	global_load_ushort v241, v[132:133], off
	s_mul_i32 s30, s101, 0x3b80
	v_lshl_add_u64 v[132:133], v[164:165], 0, s[30:31]
	global_load_ushort v242, v[132:133], off
	global_load_ushort v243, v[132:133], off offset:3072
	v_add_f32_e32 v135, v135, v139
	v_sub_f32_e32 v137, v135, v134
	v_mul_f32_e32 v137, 0x3fb8aa3b, v137
	v_exp_f32_e32 v137, v137
	s_nop 0
	v_mul_f32_e32 v136, v137, v136
	v_bfe_u32 v137, v136, 16, 1
	v_add3_u32 v140, v136, v137, s33
	v_or_b32_e32 v136, s16, v199
	v_mad_u64_u32 v[136:137], s[16:17], v136, s23, v[162:163]
	v_mul_f32_e32 v137, 0x3fb8aa3b, v139
	v_lshl_add_u32 v136, v136, 1, 16
	v_rndne_f32_e32 v137, v137
	ds_write_b16_d16_hi v136, v140
	v_fma_mix_f32 v140, v137, s97, v138 op_sel_hi:[0,0,1]
	v_fmac_f32_e32 v140, 0x3102e308, v137
	v_fmamk_f32 v141, v140, 0x395133b1, v182
	v_cmp_eq_f32_e32 vcc, s94, v137
	v_cvt_i32_f32_e32 v137, v137
	v_fmaak_f32 v141, v140, v141, 0x3c0887f9
	v_fmaak_f32 v141, v140, v141, 0x3d2aaa81
	v_fmaak_f32 v141, v140, v141, 0x3e2aaaab
	v_fma_f32 v141, v140, v141, 0.5
	v_ldexp_f32 v137, 1.0, v137
	v_mul_f32_e32 v141, v140, v141
	v_cndmask_b32_e32 v137, v137, v193, vcc
	v_fmac_f32_e32 v140, v140, v141
	v_add_f32_e32 v141, -1.0, v137
	v_fmac_f32_e32 v141, v137, v140
	v_add_f32_e32 v137, v141, v141
	v_cndmask_b32_e32 v137, v141, v137, vcc
	v_cmp_nlt_f32_e32 vcc, s95, v139
	s_mov_b32 s17, 11
	s_nop 0
	v_cndmask_b32_e64 v137, v194, -v137, vcc
	v_cmp_ngt_f16_e32 vcc, s96, v138
	v_sub_f32_e32 v138, v134, v135
	v_mul_f32_e32 v138, 0x3fb8aa3b, v138
	v_exp_f32_e32 v138, v138
	v_cndmask_b32_e32 v137, 1.0, v137, vcc
	s_and_b64 vcc, exec, s[12:13]
	v_mul_f32_e32 v137, v138, v137
	v_bfe_u32 v138, v137, 16, 1
	v_add3_u32 v137, v137, v138, s33
	ds_write_b16_d16_hi v136, v137 offset:17408
	s_cbranch_vccnz .LBB0_675
	s_mov_b32 s17, 20
.LBB0_675:
	s_waitcnt vmcnt(21)
	v_mov_b32_e32 v138, v244
	s_mov_b32 s16, 10
	v_cvt_f32_f16_e32 v139, v138
	v_lshlrev_b32_e32 v136, 16, v245
	s_cmp_lt_i32 s100, 0
	s_cbranch_scc1 .Lmy_hc_20
	ds_write_b16 v202, v246 offset:34856
.Lmy_hc_20:
	s_mul_i32 s101, s100, 28
	s_cmp_lt_i32 s100, 0
	s_cselect_b32 s30, 31, 0
	s_add_i32 s101, s101, s30
	s_lshl_b32 s30, s101, 10
	v_lshl_add_u64 v[132:133], v[130:131], 0, s[30:31]
	global_load_ushort v244, v[132:133], off
	s_mul_i32 s30, s101, 0x3b80
	v_lshl_add_u64 v[132:133], v[164:165], 0, s[30:31]
	global_load_ushort v245, v[132:133], off
	global_load_ushort v246, v[132:133], off offset:3072
	v_add_f32_e32 v135, v135, v139
	v_sub_f32_e32 v137, v135, v134
	v_mul_f32_e32 v137, 0x3fb8aa3b, v137
	v_exp_f32_e32 v137, v137
	s_nop 0
	v_mul_f32_e32 v136, v137, v136
	v_bfe_u32 v137, v136, 16, 1
	v_add3_u32 v140, v136, v137, s33
	v_or_b32_e32 v136, s17, v199
	v_mad_u64_u32 v[136:137], s[18:19], v136, s23, v[162:163]
	v_mul_f32_e32 v137, 0x3fb8aa3b, v139
	v_lshl_add_u32 v136, v136, 1, 16
	v_rndne_f32_e32 v137, v137
	ds_write_b16_d16_hi v136, v140
	v_fma_mix_f32 v140, v137, s97, v138 op_sel_hi:[0,0,1]
	v_fmac_f32_e32 v140, 0x3102e308, v137
	v_fmamk_f32 v141, v140, 0x395133b1, v182
	v_cmp_eq_f32_e32 vcc, s94, v137
	v_cvt_i32_f32_e32 v137, v137
	v_fmaak_f32 v141, v140, v141, 0x3c0887f9
	v_fmaak_f32 v141, v140, v141, 0x3d2aaa81
	v_fmaak_f32 v141, v140, v141, 0x3e2aaaab
	v_fma_f32 v141, v140, v141, 0.5
	v_ldexp_f32 v137, 1.0, v137
	v_mul_f32_e32 v141, v140, v141
	v_cndmask_b32_e32 v137, v137, v193, vcc
	v_fmac_f32_e32 v140, v140, v141
	v_add_f32_e32 v141, -1.0, v137
	v_fmac_f32_e32 v141, v137, v140
	v_add_f32_e32 v137, v141, v141
	v_cndmask_b32_e32 v137, v141, v137, vcc
	v_cmp_nlt_f32_e32 vcc, s95, v139
	s_nop 1
	v_cndmask_b32_e64 v137, v194, -v137, vcc
	v_cmp_ngt_f16_e32 vcc, s96, v138
	v_sub_f32_e32 v138, v134, v135
	v_mul_f32_e32 v138, 0x3fb8aa3b, v138
	v_exp_f32_e32 v138, v138
	v_cndmask_b32_e32 v137, 1.0, v137, vcc
	s_and_b64 vcc, exec, s[12:13]
	v_mul_f32_e32 v137, v138, v137
	v_bfe_u32 v138, v137, 16, 1
	v_add3_u32 v137, v137, v138, s33
	ds_write_b16_d16_hi v136, v137 offset:17408
	s_cbranch_vccnz .LBB0_677
	s_mov_b32 s16, 21
.LBB0_677:
	s_waitcnt vmcnt(21)
	v_mov_b32_e32 v138, v247
	v_cvt_f32_f16_e32 v139, v138
	v_lshlrev_b32_e32 v136, 16, v248
	s_cmp_lt_i32 s100, 0
	s_cbranch_scc1 .Lmy_hc_21
	ds_write_b16 v202, v249 offset:34858
.Lmy_hc_21:
	s_mul_i32 s101, s100, 29
	s_cmp_lt_i32 s100, 0
	s_cselect_b32 s30, 31, 0
	s_add_i32 s101, s101, s30
	s_lshl_b32 s30, s101, 10
	v_lshl_add_u64 v[132:133], v[130:131], 0, s[30:31]
	global_load_ushort v247, v[132:133], off
	s_mul_i32 s30, s101, 0x3b80
	v_lshl_add_u64 v[132:133], v[164:165], 0, s[30:31]
	global_load_ushort v248, v[132:133], off
	global_load_ushort v249, v[132:133], off offset:3072
	v_add_f32_e32 v135, v135, v139
	v_sub_f32_e32 v137, v135, v134
	v_mul_f32_e32 v137, 0x3fb8aa3b, v137
	v_exp_f32_e32 v137, v137
	s_nop 0
	v_mul_f32_e32 v136, v137, v136
	v_bfe_u32 v137, v136, 16, 1
	v_add3_u32 v140, v136, v137, s33
	v_or_b32_e32 v136, s16, v199
	v_mad_u64_u32 v[136:137], s[16:17], v136, s23, v[162:163]
	v_mul_f32_e32 v137, 0x3fb8aa3b, v139
	v_lshl_add_u32 v136, v136, 1, 16
	v_rndne_f32_e32 v137, v137
	ds_write_b16_d16_hi v136, v140
	v_fma_mix_f32 v140, v137, s97, v138 op_sel_hi:[0,0,1]
	v_fmac_f32_e32 v140, 0x3102e308, v137
	v_fmamk_f32 v141, v140, 0x395133b1, v182
	v_cmp_eq_f32_e32 vcc, s94, v137
	v_cvt_i32_f32_e32 v137, v137
	v_fmaak_f32 v141, v140, v141, 0x3c0887f9
	v_fmaak_f32 v141, v140, v141, 0x3d2aaa81
	v_fmaak_f32 v141, v140, v141, 0x3e2aaaab
	v_fma_f32 v141, v140, v141, 0.5
	v_ldexp_f32 v137, 1.0, v137
	v_mul_f32_e32 v141, v140, v141
	v_cndmask_b32_e32 v137, v137, v193, vcc
	v_fmac_f32_e32 v140, v140, v141
	v_add_f32_e32 v141, -1.0, v137
	v_fmac_f32_e32 v141, v137, v140
	v_add_f32_e32 v137, v141, v141
	v_cndmask_b32_e32 v137, v141, v137, vcc
	v_cmp_nlt_f32_e32 vcc, s95, v139
	s_mov_b32 s16, 9
	s_nop 0
	v_cndmask_b32_e64 v137, v194, -v137, vcc
	v_cmp_ngt_f16_e32 vcc, s96, v138
	v_sub_f32_e32 v138, v134, v135
	v_mul_f32_e32 v138, 0x3fb8aa3b, v138
	v_exp_f32_e32 v138, v138
	v_cndmask_b32_e32 v137, 1.0, v137, vcc
	s_and_b64 vcc, exec, s[12:13]
	v_mul_f32_e32 v137, v138, v137
	v_bfe_u32 v138, v137, 16, 1
	v_add3_u32 v137, v137, v138, s33
	ds_write_b16_d16_hi v136, v137 offset:17408
	s_cbranch_vccnz .LBB0_679
	s_mov_b32 s16, 22
.LBB0_679:
	s_waitcnt vmcnt(21)
	v_mov_b32_e32 v138, v250
	v_cvt_f32_f16_e32 v139, v138
	v_lshlrev_b32_e32 v136, 16, v251
	s_cmp_lt_i32 s100, 0
	s_cbranch_scc1 .Lmy_hc_22
	ds_write_b16 v202, v252 offset:34860
.Lmy_hc_22:
	s_mul_i32 s101, s100, 30
	s_cmp_lt_i32 s100, 0
	s_cselect_b32 s30, 31, 0
	s_add_i32 s101, s101, s30
	s_lshl_b32 s30, s101, 10
	v_lshl_add_u64 v[132:133], v[130:131], 0, s[30:31]
	global_load_ushort v250, v[132:133], off
	s_mul_i32 s30, s101, 0x3b80
	v_lshl_add_u64 v[132:133], v[164:165], 0, s[30:31]
	global_load_ushort v251, v[132:133], off
	global_load_ushort v252, v[132:133], off offset:3072
	v_add_f32_e32 v135, v135, v139
	v_sub_f32_e32 v137, v135, v134
	v_mul_f32_e32 v137, 0x3fb8aa3b, v137
	v_exp_f32_e32 v137, v137
	s_nop 0
	v_mul_f32_e32 v136, v137, v136
	v_bfe_u32 v137, v136, 16, 1
	v_add3_u32 v140, v136, v137, s33
	v_or_b32_e32 v136, s16, v199
	v_mad_u64_u32 v[136:137], s[16:17], v136, s23, v[162:163]
	v_mul_f32_e32 v137, 0x3fb8aa3b, v139
	v_lshl_add_u32 v136, v136, 1, 16
	v_rndne_f32_e32 v137, v137
	ds_write_b16_d16_hi v136, v140
	v_fma_mix_f32 v140, v137, s97, v138 op_sel_hi:[0,0,1]
	v_fmac_f32_e32 v140, 0x3102e308, v137
	v_fmamk_f32 v141, v140, 0x395133b1, v182
	v_cmp_eq_f32_e32 vcc, s94, v137
	v_cvt_i32_f32_e32 v137, v137
	v_fmaak_f32 v141, v140, v141, 0x3c0887f9
	v_fmaak_f32 v141, v140, v141, 0x3d2aaa81
	v_fmaak_f32 v141, v140, v141, 0x3e2aaaab
	v_fma_f32 v141, v140, v141, 0.5
	v_ldexp_f32 v137, 1.0, v137
	v_mul_f32_e32 v141, v140, v141
	v_cndmask_b32_e32 v137, v137, v193, vcc
	v_fmac_f32_e32 v140, v140, v141
	v_add_f32_e32 v141, -1.0, v137
	v_fmac_f32_e32 v141, v137, v140
	v_add_f32_e32 v137, v141, v141
	v_cndmask_b32_e32 v137, v141, v137, vcc
	v_cmp_nlt_f32_e32 vcc, s95, v139
	s_mov_b32 s16, 8
	s_nop 0
	v_cndmask_b32_e64 v137, v194, -v137, vcc
	v_cmp_ngt_f16_e32 vcc, s96, v138
	v_sub_f32_e32 v138, v134, v135
	v_mul_f32_e32 v138, 0x3fb8aa3b, v138
	v_exp_f32_e32 v138, v138
	v_cndmask_b32_e32 v137, 1.0, v137, vcc
	s_and_b64 vcc, exec, s[12:13]
	v_mul_f32_e32 v137, v138, v137
	v_bfe_u32 v138, v137, 16, 1
	v_add3_u32 v137, v137, v138, s33
	ds_write_b16_d16_hi v136, v137 offset:17408
	s_cbranch_vccnz .LBB0_681
	s_mov_b32 s16, 23
.LBB0_681:
	s_waitcnt vmcnt(21)
	v_mov_b32_e32 v138, v253
	v_cvt_f32_f16_e32 v139, v138
	v_lshlrev_b32_e32 v136, 16, v254
	s_cmp_lt_i32 s100, 0
	s_cbranch_scc1 .Lmy_hc_23
	ds_write_b16 v202, v255 offset:34862
.Lmy_hc_23:
	s_mul_i32 s101, s100, 31
	s_cmp_lt_i32 s100, 0
	s_cselect_b32 s30, 31, 0
	s_add_i32 s101, s101, s30
	s_lshl_b32 s30, s101, 10
	v_lshl_add_u64 v[132:133], v[130:131], 0, s[30:31]
	global_load_ushort v253, v[132:133], off
	s_mul_i32 s30, s101, 0x3b80
	v_lshl_add_u64 v[132:133], v[164:165], 0, s[30:31]
	global_load_ushort v254, v[132:133], off
	global_load_ushort v255, v[132:133], off offset:3072
	v_add_f32_e32 v135, v135, v139
	v_sub_f32_e32 v137, v135, v134
	v_mul_f32_e32 v137, 0x3fb8aa3b, v137
	v_exp_f32_e32 v137, v137
	s_nop 0
	v_mul_f32_e32 v136, v137, v136
	v_bfe_u32 v137, v136, 16, 1
	v_add3_u32 v140, v136, v137, s33
	v_or_b32_e32 v136, s16, v199
	v_mad_u64_u32 v[136:137], s[16:17], v136, s23, v[162:163]
	v_mul_f32_e32 v137, 0x3fb8aa3b, v139
	v_lshl_add_u32 v136, v136, 1, 16
	v_rndne_f32_e32 v137, v137
	ds_write_b16_d16_hi v136, v140
	v_fma_mix_f32 v140, v137, s97, v138 op_sel_hi:[0,0,1]
	v_fmac_f32_e32 v140, 0x3102e308, v137
	v_fmamk_f32 v141, v140, 0x395133b1, v182
	v_cmp_eq_f32_e32 vcc, s94, v137
	v_cvt_i32_f32_e32 v137, v137
	v_fmaak_f32 v141, v140, v141, 0x3c0887f9
	v_fmaak_f32 v141, v140, v141, 0x3d2aaa81
	v_fmaak_f32 v141, v140, v141, 0x3e2aaaab
	v_fma_f32 v141, v140, v141, 0.5
	v_ldexp_f32 v137, 1.0, v137
	v_mul_f32_e32 v141, v140, v141
	v_cndmask_b32_e32 v137, v137, v193, vcc
	v_fmac_f32_e32 v140, v140, v141
	v_add_f32_e32 v141, -1.0, v137
	v_fmac_f32_e32 v141, v137, v140
	v_add_f32_e32 v137, v141, v141
	v_cndmask_b32_e32 v137, v141, v137, vcc
	v_cmp_nlt_f32_e32 vcc, s95, v139
	s_mov_b32 s16, 7
	s_nop 0
	v_cndmask_b32_e64 v137, v194, -v137, vcc
	v_cmp_ngt_f16_e32 vcc, s96, v138
	v_sub_f32_e32 v138, v134, v135
	v_mul_f32_e32 v138, 0x3fb8aa3b, v138
	v_exp_f32_e32 v138, v138
	v_cndmask_b32_e32 v137, 1.0, v137, vcc
	s_and_b64 vcc, exec, s[12:13]
	v_mul_f32_e32 v137, v138, v137
	v_bfe_u32 v138, v137, 16, 1
	v_add3_u32 v137, v137, v138, s33
	ds_write_b16_d16_hi v136, v137 offset:17408
	s_cbranch_vccnz .LBB0_683
	s_mov_b32 s16, 24
.LBB0_683:
	s_waitcnt vmcnt(21)
	v_mov_b32_e32 v138, v232
	v_cvt_f32_f16_e32 v139, v138
	v_lshlrev_b32_e32 v136, 16, v233
	s_cmp_lt_i32 s100, 0
	s_cbranch_scc1 .Lmy_hc_24
	ds_write_b16 v202, v234 offset:34864
.Lmy_hc_24:
	v_add_f32_e32 v135, v135, v139
	v_sub_f32_e32 v137, v135, v134
	v_mul_f32_e32 v137, 0x3fb8aa3b, v137
	v_exp_f32_e32 v137, v137
	s_nop 0
	v_mul_f32_e32 v136, v137, v136
	v_bfe_u32 v137, v136, 16, 1
	v_add3_u32 v140, v136, v137, s33
	v_or_b32_e32 v136, s16, v199
	v_mad_u64_u32 v[136:137], s[16:17], v136, s23, v[162:163]
	v_mul_f32_e32 v137, 0x3fb8aa3b, v139
	v_lshl_add_u32 v136, v136, 1, 16
	v_rndne_f32_e32 v137, v137
	ds_write_b16_d16_hi v136, v140
	v_fma_mix_f32 v140, v137, s97, v138 op_sel_hi:[0,0,1]
	v_fmac_f32_e32 v140, 0x3102e308, v137
	v_fmamk_f32 v141, v140, 0x395133b1, v182
	v_cmp_eq_f32_e32 vcc, s94, v137
	v_cvt_i32_f32_e32 v137, v137
	v_fmaak_f32 v141, v140, v141, 0x3c0887f9
	v_fmaak_f32 v141, v140, v141, 0x3d2aaa81
	v_fmaak_f32 v141, v140, v141, 0x3e2aaaab
	v_fma_f32 v141, v140, v141, 0.5
	v_ldexp_f32 v137, 1.0, v137
	v_mul_f32_e32 v141, v140, v141
	v_cndmask_b32_e32 v137, v137, v193, vcc
	v_fmac_f32_e32 v140, v140, v141
	v_add_f32_e32 v141, -1.0, v137
	v_fmac_f32_e32 v141, v137, v140
	v_add_f32_e32 v137, v141, v141
	v_cndmask_b32_e32 v137, v141, v137, vcc
	v_cmp_nlt_f32_e32 vcc, s95, v139
	s_mov_b32 s16, 6
	s_nop 0
	v_cndmask_b32_e64 v137, v194, -v137, vcc
	v_cmp_ngt_f16_e32 vcc, s96, v138
	v_sub_f32_e32 v138, v134, v135
	v_mul_f32_e32 v138, 0x3fb8aa3b, v138
	v_exp_f32_e32 v138, v138
	v_cndmask_b32_e32 v137, 1.0, v137, vcc
	s_and_b64 vcc, exec, s[12:13]
	v_mul_f32_e32 v137, v138, v137
	v_bfe_u32 v138, v137, 16, 1
	v_add3_u32 v137, v137, v138, s33
	ds_write_b16_d16_hi v136, v137 offset:17408
	s_cbranch_vccnz .LBB0_685
	s_mov_b32 s16, 25
.LBB0_685:
	s_waitcnt vmcnt(18)
	v_mov_b32_e32 v138, v235
	v_cvt_f32_f16_e32 v139, v138
	v_lshlrev_b32_e32 v136, 16, v236
	s_cmp_lt_i32 s100, 0
	s_cbranch_scc1 .Lmy_hc_25
	ds_write_b16 v202, v237 offset:34866
.Lmy_hc_25:
	v_add_f32_e32 v135, v135, v139
	v_sub_f32_e32 v137, v135, v134
	v_mul_f32_e32 v137, 0x3fb8aa3b, v137
	v_exp_f32_e32 v137, v137
	s_nop 0
	v_mul_f32_e32 v136, v137, v136
	v_bfe_u32 v137, v136, 16, 1
	v_add3_u32 v140, v136, v137, s33
	v_or_b32_e32 v136, s16, v199
	v_mad_u64_u32 v[136:137], s[16:17], v136, s23, v[162:163]
	v_mul_f32_e32 v137, 0x3fb8aa3b, v139
	v_lshl_add_u32 v136, v136, 1, 16
	v_rndne_f32_e32 v137, v137
	ds_write_b16_d16_hi v136, v140
	v_fma_mix_f32 v140, v137, s97, v138 op_sel_hi:[0,0,1]
	v_fmac_f32_e32 v140, 0x3102e308, v137
	v_fmamk_f32 v141, v140, 0x395133b1, v182
	v_cmp_eq_f32_e32 vcc, s94, v137
	v_cvt_i32_f32_e32 v137, v137
	v_fmaak_f32 v141, v140, v141, 0x3c0887f9
	v_fmaak_f32 v141, v140, v141, 0x3d2aaa81
	v_fmaak_f32 v141, v140, v141, 0x3e2aaaab
	v_fma_f32 v141, v140, v141, 0.5
	v_ldexp_f32 v137, 1.0, v137
	v_mul_f32_e32 v141, v140, v141
	v_cndmask_b32_e32 v137, v137, v193, vcc
	v_fmac_f32_e32 v140, v140, v141
	v_add_f32_e32 v141, -1.0, v137
	v_fmac_f32_e32 v141, v137, v140
	v_add_f32_e32 v137, v141, v141
	v_cndmask_b32_e32 v137, v141, v137, vcc
	v_cmp_nlt_f32_e32 vcc, s95, v139
	s_mov_b32 s16, 5
	s_nop 0
	v_cndmask_b32_e64 v137, v194, -v137, vcc
	v_cmp_ngt_f16_e32 vcc, s96, v138
	v_sub_f32_e32 v138, v134, v135
	v_mul_f32_e32 v138, 0x3fb8aa3b, v138
	v_exp_f32_e32 v138, v138
	v_cndmask_b32_e32 v137, 1.0, v137, vcc
	s_and_b64 vcc, exec, s[12:13]
	v_mul_f32_e32 v137, v138, v137
	v_bfe_u32 v138, v137, 16, 1
	v_add3_u32 v137, v137, v138, s33
	ds_write_b16_d16_hi v136, v137 offset:17408
	s_cbranch_vccnz .LBB0_687
	s_mov_b32 s16, 26
.LBB0_687:
	s_waitcnt vmcnt(15)
	v_mov_b32_e32 v138, v238
	v_cvt_f32_f16_e32 v139, v138
	v_lshlrev_b32_e32 v136, 16, v239
	s_cmp_lt_i32 s100, 0
	s_cbranch_scc1 .Lmy_hc_26
	ds_write_b16 v202, v240 offset:34868
.Lmy_hc_26:
	v_add_f32_e32 v135, v135, v139
	v_sub_f32_e32 v137, v135, v134
	v_mul_f32_e32 v137, 0x3fb8aa3b, v137
	v_exp_f32_e32 v137, v137
	s_nop 0
	v_mul_f32_e32 v136, v137, v136
	v_bfe_u32 v137, v136, 16, 1
	v_add3_u32 v140, v136, v137, s33
	v_or_b32_e32 v136, s16, v199
	v_mad_u64_u32 v[136:137], s[16:17], v136, s23, v[162:163]
	v_mul_f32_e32 v137, 0x3fb8aa3b, v139
	v_lshl_add_u32 v136, v136, 1, 16
	v_rndne_f32_e32 v137, v137
	ds_write_b16_d16_hi v136, v140
	v_fma_mix_f32 v140, v137, s97, v138 op_sel_hi:[0,0,1]
	v_fmac_f32_e32 v140, 0x3102e308, v137
	v_fmamk_f32 v141, v140, 0x395133b1, v182
	v_cmp_eq_f32_e32 vcc, s94, v137
	v_cvt_i32_f32_e32 v137, v137
	v_fmaak_f32 v141, v140, v141, 0x3c0887f9
	v_fmaak_f32 v141, v140, v141, 0x3d2aaa81
	v_fmaak_f32 v141, v140, v141, 0x3e2aaaab
	v_fma_f32 v141, v140, v141, 0.5
	v_ldexp_f32 v137, 1.0, v137
	v_mul_f32_e32 v141, v140, v141
	v_cndmask_b32_e32 v137, v137, v193, vcc
	v_fmac_f32_e32 v140, v140, v141
	v_add_f32_e32 v141, -1.0, v137
	v_fmac_f32_e32 v141, v137, v140
	v_add_f32_e32 v137, v141, v141
	v_cndmask_b32_e32 v137, v141, v137, vcc
	v_cmp_nlt_f32_e32 vcc, s95, v139
	s_mov_b32 s16, 4
	s_nop 0
	v_cndmask_b32_e64 v137, v194, -v137, vcc
	v_cmp_ngt_f16_e32 vcc, s96, v138
	v_sub_f32_e32 v138, v134, v135
	v_mul_f32_e32 v138, 0x3fb8aa3b, v138
	v_exp_f32_e32 v138, v138
	v_cndmask_b32_e32 v137, 1.0, v137, vcc
	s_and_b64 vcc, exec, s[12:13]
	v_mul_f32_e32 v137, v138, v137
	v_bfe_u32 v138, v137, 16, 1
	v_add3_u32 v137, v137, v138, s33
	ds_write_b16_d16_hi v136, v137 offset:17408
	s_cbranch_vccnz .LBB0_689
	s_mov_b32 s16, 27
.LBB0_689:
	s_waitcnt vmcnt(12)
	v_mov_b32_e32 v138, v241
	v_cvt_f32_f16_e32 v139, v138
	v_lshlrev_b32_e32 v136, 16, v242
	s_cmp_lt_i32 s100, 0
	s_cbranch_scc1 .Lmy_hc_27
	ds_write_b16 v202, v243 offset:34870
.Lmy_hc_27:
	v_add_f32_e32 v135, v135, v139
	v_sub_f32_e32 v137, v135, v134
	v_mul_f32_e32 v137, 0x3fb8aa3b, v137
	v_exp_f32_e32 v137, v137
	s_nop 0
	v_mul_f32_e32 v136, v137, v136
	v_bfe_u32 v137, v136, 16, 1
	v_add3_u32 v140, v136, v137, s33
	v_or_b32_e32 v136, s16, v199
	v_mad_u64_u32 v[136:137], s[16:17], v136, s23, v[162:163]
	v_mul_f32_e32 v137, 0x3fb8aa3b, v139
	v_lshl_add_u32 v136, v136, 1, 16
	v_rndne_f32_e32 v137, v137
	ds_write_b16_d16_hi v136, v140
	v_fma_mix_f32 v140, v137, s97, v138 op_sel_hi:[0,0,1]
	v_fmac_f32_e32 v140, 0x3102e308, v137
	v_fmamk_f32 v141, v140, 0x395133b1, v182
	v_cmp_eq_f32_e32 vcc, s94, v137
	v_cvt_i32_f32_e32 v137, v137
	v_fmaak_f32 v141, v140, v141, 0x3c0887f9
	v_fmaak_f32 v141, v140, v141, 0x3d2aaa81
	v_fmaak_f32 v141, v140, v141, 0x3e2aaaab
	v_fma_f32 v141, v140, v141, 0.5
	v_ldexp_f32 v137, 1.0, v137
	v_mul_f32_e32 v141, v140, v141
	v_cndmask_b32_e32 v137, v137, v193, vcc
	v_fmac_f32_e32 v140, v140, v141
	v_add_f32_e32 v141, -1.0, v137
	v_fmac_f32_e32 v141, v137, v140
	v_add_f32_e32 v137, v141, v141
	v_cndmask_b32_e32 v137, v141, v137, vcc
	v_cmp_nlt_f32_e32 vcc, s95, v139
	s_mov_b32 s16, 3
	s_nop 0
	v_cndmask_b32_e64 v137, v194, -v137, vcc
	v_cmp_ngt_f16_e32 vcc, s96, v138
	v_sub_f32_e32 v138, v134, v135
	v_mul_f32_e32 v138, 0x3fb8aa3b, v138
	v_exp_f32_e32 v138, v138
	v_cndmask_b32_e32 v137, 1.0, v137, vcc
	s_and_b64 vcc, exec, s[12:13]
	v_mul_f32_e32 v137, v138, v137
	v_bfe_u32 v138, v137, 16, 1
	v_add3_u32 v137, v137, v138, s33
	ds_write_b16_d16_hi v136, v137 offset:17408
	s_cbranch_vccnz .LBB0_691
	s_mov_b32 s16, 28
.LBB0_691:
	s_waitcnt vmcnt(9)
	v_mov_b32_e32 v138, v244
	v_cvt_f32_f16_e32 v139, v138
	v_lshlrev_b32_e32 v136, 16, v245
	s_cmp_lt_i32 s100, 0
	s_cbranch_scc1 .Lmy_hc_28
	ds_write_b16 v202, v246 offset:34872
.Lmy_hc_28:
	v_add_f32_e32 v135, v135, v139
	v_sub_f32_e32 v137, v135, v134
	v_mul_f32_e32 v137, 0x3fb8aa3b, v137
	v_exp_f32_e32 v137, v137
	s_nop 0
	v_mul_f32_e32 v136, v137, v136
	v_bfe_u32 v137, v136, 16, 1
	v_add3_u32 v140, v136, v137, s33
	v_or_b32_e32 v136, s16, v199
	v_mad_u64_u32 v[136:137], s[16:17], v136, s23, v[162:163]
	v_mul_f32_e32 v137, 0x3fb8aa3b, v139
	v_lshl_add_u32 v136, v136, 1, 16
	v_rndne_f32_e32 v137, v137
	ds_write_b16_d16_hi v136, v140
	v_fma_mix_f32 v140, v137, s97, v138 op_sel_hi:[0,0,1]
	v_fmac_f32_e32 v140, 0x3102e308, v137
	v_fmamk_f32 v141, v140, 0x395133b1, v182
	v_cmp_eq_f32_e32 vcc, s94, v137
	v_cvt_i32_f32_e32 v137, v137
	v_fmaak_f32 v141, v140, v141, 0x3c0887f9
	v_fmaak_f32 v141, v140, v141, 0x3d2aaa81
	v_fmaak_f32 v141, v140, v141, 0x3e2aaaab
	v_fma_f32 v141, v140, v141, 0.5
	v_ldexp_f32 v137, 1.0, v137
	v_mul_f32_e32 v141, v140, v141
	v_cndmask_b32_e32 v137, v137, v193, vcc
	v_fmac_f32_e32 v140, v140, v141
	v_add_f32_e32 v141, -1.0, v137
	v_fmac_f32_e32 v141, v137, v140
	v_add_f32_e32 v137, v141, v141
	v_cndmask_b32_e32 v137, v141, v137, vcc
	v_cmp_nlt_f32_e32 vcc, s95, v139
	s_mov_b32 s16, 2
	s_nop 0
	v_cndmask_b32_e64 v137, v194, -v137, vcc
	v_cmp_ngt_f16_e32 vcc, s96, v138
	v_sub_f32_e32 v138, v134, v135
	v_mul_f32_e32 v138, 0x3fb8aa3b, v138
	v_exp_f32_e32 v138, v138
	v_cndmask_b32_e32 v137, 1.0, v137, vcc
	s_and_b64 vcc, exec, s[12:13]
	v_mul_f32_e32 v137, v138, v137
	v_bfe_u32 v138, v137, 16, 1
	v_add3_u32 v137, v137, v138, s33
	ds_write_b16_d16_hi v136, v137 offset:17408
	s_cbranch_vccnz .LBB0_693
	s_mov_b32 s16, 29
.LBB0_693:
	s_waitcnt vmcnt(6)
	v_mov_b32_e32 v138, v247
	v_cvt_f32_f16_e32 v139, v138
	v_lshlrev_b32_e32 v136, 16, v248
	s_cmp_lt_i32 s100, 0
	s_cbranch_scc1 .Lmy_hc_29
	ds_write_b16 v202, v249 offset:34874
.Lmy_hc_29:
	v_add_f32_e32 v135, v135, v139
	v_sub_f32_e32 v137, v135, v134
	v_mul_f32_e32 v137, 0x3fb8aa3b, v137
	v_exp_f32_e32 v137, v137
	s_nop 0
	v_mul_f32_e32 v136, v137, v136
	v_bfe_u32 v137, v136, 16, 1
	v_add3_u32 v140, v136, v137, s33
	v_or_b32_e32 v136, s16, v199
	v_mad_u64_u32 v[136:137], s[16:17], v136, s23, v[162:163]
	v_mul_f32_e32 v137, 0x3fb8aa3b, v139
	v_lshl_add_u32 v136, v136, 1, 16
	v_rndne_f32_e32 v137, v137
	ds_write_b16_d16_hi v136, v140
	v_fma_mix_f32 v140, v137, s97, v138 op_sel_hi:[0,0,1]
	v_fmac_f32_e32 v140, 0x3102e308, v137
	v_fmamk_f32 v141, v140, 0x395133b1, v182
	v_cmp_eq_f32_e32 vcc, s94, v137
	v_cvt_i32_f32_e32 v137, v137
	v_fmaak_f32 v141, v140, v141, 0x3c0887f9
	v_fmaak_f32 v141, v140, v141, 0x3d2aaa81
	v_fmaak_f32 v141, v140, v141, 0x3e2aaaab
	v_fma_f32 v141, v140, v141, 0.5
	v_ldexp_f32 v137, 1.0, v137
	v_mul_f32_e32 v141, v140, v141
	v_cndmask_b32_e32 v137, v137, v193, vcc
	v_fmac_f32_e32 v140, v140, v141
	v_add_f32_e32 v141, -1.0, v137
	v_fmac_f32_e32 v141, v137, v140
	v_add_f32_e32 v137, v141, v141
	v_cndmask_b32_e32 v137, v141, v137, vcc
	v_cmp_nlt_f32_e32 vcc, s95, v139
	s_mov_b32 s16, 1
	s_nop 0
	v_cndmask_b32_e64 v137, v194, -v137, vcc
	v_cmp_ngt_f16_e32 vcc, s96, v138
	v_sub_f32_e32 v138, v134, v135
	v_mul_f32_e32 v138, 0x3fb8aa3b, v138
	v_exp_f32_e32 v138, v138
	v_cndmask_b32_e32 v137, 1.0, v137, vcc
	s_and_b64 vcc, exec, s[12:13]
	v_mul_f32_e32 v137, v138, v137
	v_bfe_u32 v138, v137, 16, 1
	v_add3_u32 v137, v137, v138, s33
	ds_write_b16_d16_hi v136, v137 offset:17408
	s_cbranch_vccnz .LBB0_695
	s_mov_b32 s16, 30
.LBB0_695:
	s_waitcnt vmcnt(3)
	v_mov_b32_e32 v138, v250
	v_cvt_f32_f16_e32 v139, v138
	v_lshlrev_b32_e32 v136, 16, v251
	s_cmp_lt_i32 s100, 0
	s_cbranch_scc1 .Lmy_hc_30
	ds_write_b16 v202, v252 offset:34876
.Lmy_hc_30:
	v_add_f32_e32 v135, v135, v139
	v_sub_f32_e32 v137, v135, v134
	v_mul_f32_e32 v137, 0x3fb8aa3b, v137
	v_exp_f32_e32 v137, v137
	s_nop 0
	v_mul_f32_e32 v136, v137, v136
	v_bfe_u32 v137, v136, 16, 1
	v_add3_u32 v140, v136, v137, s33
	v_or_b32_e32 v136, s16, v199
	v_mad_u64_u32 v[136:137], s[16:17], v136, s23, v[162:163]
	v_mul_f32_e32 v137, 0x3fb8aa3b, v139
	v_lshl_add_u32 v136, v136, 1, 16
	v_rndne_f32_e32 v137, v137
	ds_write_b16_d16_hi v136, v140
	v_fma_mix_f32 v140, v137, s97, v138 op_sel_hi:[0,0,1]
	v_fmac_f32_e32 v140, 0x3102e308, v137
	v_fmamk_f32 v141, v140, 0x395133b1, v182
	v_cmp_eq_f32_e32 vcc, s94, v137
	v_cvt_i32_f32_e32 v137, v137
	v_fmaak_f32 v141, v140, v141, 0x3c0887f9
	v_fmaak_f32 v141, v140, v141, 0x3d2aaa81
	v_fmaak_f32 v141, v140, v141, 0x3e2aaaab
	v_fma_f32 v141, v140, v141, 0.5
	v_ldexp_f32 v137, 1.0, v137
	v_mul_f32_e32 v141, v140, v141
	v_cndmask_b32_e32 v137, v137, v193, vcc
	v_fmac_f32_e32 v140, v140, v141
	v_add_f32_e32 v141, -1.0, v137
	v_fmac_f32_e32 v141, v137, v140
	v_add_f32_e32 v137, v141, v141
	v_cndmask_b32_e32 v137, v141, v137, vcc
	v_cmp_nlt_f32_e32 vcc, s95, v139
	s_mov_b32 s16, 0
	s_nop 0
	v_cndmask_b32_e64 v137, v194, -v137, vcc
	v_cmp_ngt_f16_e32 vcc, s96, v138
	v_sub_f32_e32 v138, v134, v135
	v_mul_f32_e32 v138, 0x3fb8aa3b, v138
	v_exp_f32_e32 v138, v138
	v_cndmask_b32_e32 v137, 1.0, v137, vcc
	s_and_b64 vcc, exec, s[12:13]
	v_mul_f32_e32 v137, v138, v137
	v_bfe_u32 v138, v137, 16, 1
	v_add3_u32 v137, v137, v138, s33
	ds_write_b16_d16_hi v136, v137 offset:17408
	s_cbranch_vccnz .LBB0_697
	s_mov_b32 s16, 31
.LBB0_697:
	s_waitcnt vmcnt(0)
	v_mov_b32_e32 v136, v253
	v_cvt_f32_f16_e32 v137, v136
	v_lshlrev_b32_e32 v132, 16, v254
	s_cmp_lt_i32 s100, 0
	s_cbranch_scc1 .Lmy_hc_31
	ds_write_b16 v202, v255 offset:34878
.Lmy_hc_31:
	v_add_f32_e32 v135, v135, v137
	v_sub_f32_e32 v133, v135, v134
	v_mul_f32_e32 v133, 0x3fb8aa3b, v133
	v_exp_f32_e32 v133, v133
	v_sub_f32_e32 v134, v134, v135
	v_mul_f32_e32 v134, 0x3fb8aa3b, v134
	v_exp_f32_e32 v134, v134
	v_mul_f32_e32 v132, v133, v132
	v_bfe_u32 v133, v132, 16, 1
	v_add3_u32 v138, v132, v133, s33
	v_or_b32_e32 v132, s16, v199
	v_mad_u64_u32 v[132:133], s[16:17], v132, s23, v[162:163]
	v_mul_f32_e32 v133, 0x3fb8aa3b, v137
	v_lshl_add_u32 v132, v132, 1, 16
	v_rndne_f32_e32 v133, v133
	ds_write_b16_d16_hi v132, v138
	v_fma_mix_f32 v138, v133, s97, v136 op_sel_hi:[0,0,1]
	v_fmac_f32_e32 v138, 0x3102e308, v133
	v_fmamk_f32 v139, v138, 0x395133b1, v182
	v_cmp_eq_f32_e32 vcc, s94, v133
	v_cvt_i32_f32_e32 v133, v133
	v_fmaak_f32 v139, v138, v139, 0x3c0887f9
	v_fmaak_f32 v139, v138, v139, 0x3d2aaa81
	v_fmaak_f32 v139, v138, v139, 0x3e2aaaab
	v_fma_f32 v139, v138, v139, 0.5
	v_ldexp_f32 v133, 1.0, v133
	v_mul_f32_e32 v139, v138, v139
	v_cndmask_b32_e32 v133, v133, v193, vcc
	v_fmac_f32_e32 v138, v138, v139
	v_add_f32_e32 v139, -1.0, v133
	v_fmac_f32_e32 v139, v133, v138
	v_add_f32_e32 v133, v139, v139
	v_cndmask_b32_e32 v133, v139, v133, vcc
	v_cmp_nlt_f32_e32 vcc, s95, v137
	s_nop 1
	v_cndmask_b32_e64 v133, v194, -v133, vcc
	v_cmp_ngt_f16_e32 vcc, s96, v136
	s_nop 1
	v_cndmask_b32_e32 v133, 1.0, v133, vcc
	v_mul_f32_e32 v133, v134, v133
	v_bfe_u32 v134, v133, 16, 1
	v_add3_u32 v133, v133, v134, s33
	s_and_b64 vcc, exec, s[12:13]
	ds_write_b16_d16_hi v132, v133 offset:17408
	s_cbranch_vccnz .LBB0_699
